# v6: + gla_scan loads in flight + norm slab/gate loads batched
# speedup vs baseline: 1.0355x; 1.0055x over previous
; __device__ __forceinline__ unsigned pk_bf16(float lo, float hi) { unsigned r; asm volatile("v_cvt_pk_bf16_f32 %0, %1, %2" : "=v"(r) : "v"(lo), "v"(hi)); return r; }
; __device__ __forceinline__ float bflo(unsigned w) { return __uint_as_float(w << 16); }
; __device__ __forceinline__ float bfhi(unsigned w) { return __uint_as_float(w & 0xffff0000u); }
; __device__ __forceinline__ void phase_norm(int wv, const Params& p, int l, int which, int nrows, int nparts, const float* rgate) {
;     ...
;                 if (!lat && nparts > 0) {
; #pragma unroll
;                     for (int jj = 0; jj < 2; ++jj) { f32x4 s0 = (f32x4){0.f, 0.f, 0.f, 0.f}, s1 = s0;
;                         for (int pt = 0; pt < nparts; ++pt) { const u32x4 w = *(const u32x4*)((const bf16_t*)(p.ws + OFF_S) + (size_t)pt * 2048 * 1024 + (size_t)(row - MLAT) * 1024 + jj * 512 + lane * 8);
;                             s0 += (f32x4){bflo(w.x), bfhi(w.x), bflo(w.y), bfhi(w.y)}; s1 += (f32x4){bflo(w.z), bfhi(w.z), bflo(w.w), bfhi(w.w)}; }
;                         v[u][2 * jj] += *(const f32x4*)(rgate + cq[2 * jj]) * s0; v[u][2 * jj + 1] += *(const f32x4*)(rgate + cq[2 * jj + 1]) * s1;
;                         u32x4 w; w.x = pk_bf16(v[u][2 * jj][0], v[u][2 * jj][1]); w.y = pk_bf16(v[u][2 * jj][2], v[u][2 * jj][3]); w.z = pk_bf16(v[u][2 * jj + 1][0], v[u][2 * jj + 1][1]); w.w = pk_bf16(v[u][2 * jj + 1][2], v[u][2 * jj + 1][3]);
;                         *(u32x4*)((bf16_t*)(p.ws + OFF_XB) + (size_t)row * 1024 + jj * 512 + lane * 8) = w; } }
.LBB0_102:
	s_or_b64 exec, exec, s[6:7]
	v_readlane_b32 s0, v255, 20
	v_cmp_lt_i32_e64 s[14:15], s46, v120
	v_readlane_b32 s1, v255, 21
	s_and_b64 s[0:1], s[14:15], s[0:1]
	s_xor_b64 s[0:1], s[0:1], -1
	s_and_saveexec_b64 s[4:5], s[0:1]
	s_xor_b64 s[4:5], exec, s[4:5]
	v_mov_b32_e32 v121, v1
	v_lshlrev_b64 v[2:3], 11, v[120:121]
	s_andn2_saveexec_b64 s[6:7], s[4:5]
	s_cbranch_execz .LBB0_106
	v_mov_b32_e32 v99, v1
	v_lshlrev_b64 v[126:127], 11, v[98:99]
	v_lshl_add_u64 v[2:3], v[94:95], 0, v[126:127]
	global_load_dwordx4 v[52:55], v[2:3], off
	v_add_co_u32_e32 v168, vcc, s47, v2
	s_nop 1
	v_addc_co_u32_e32 v169, vcc, 0, v3, vcc
	global_load_dwordx4 v[144:147], v[168:169], off
	v_add_co_u32_e32 v168, vcc, s68, v2
	s_nop 1
	v_addc_co_u32_e32 v169, vcc, 0, v3, vcc
	global_load_dwordx4 v[148:151], v[168:169], off
	v_add_co_u32_e32 v168, vcc, s48, v2
	s_nop 1
	v_addc_co_u32_e32 v169, vcc, 0, v3, vcc
	global_load_dwordx4 v[152:155], v[168:169], off
	v_add_co_u32_e32 v168, vcc, s49, v2
	s_nop 1
	v_addc_co_u32_e32 v169, vcc, 0, v3, vcc
	global_load_dwordx4 v[156:159], v[168:169], off
	global_load_dwordx4 v[160:163], v[72:73], off
	global_load_dwordx4 v[164:167], v[74:75], off
	v_mov_b32_e32 v121, v1
	v_lshlrev_b32_e32 v0, 1, v58
	s_waitcnt vmcnt(0)
	v_lshlrev_b32_e32 v128, 16, v52
	v_and_b32_e32 v129, 0xffff0000, v52
	v_lshlrev_b32_e32 v52, 16, v53
	v_and_b32_e32 v53, 0xffff0000, v53
	v_pk_add_f32 v[130:131], v[52:53], 0 op_sel_hi:[1,0]
	v_lshlrev_b32_e32 v52, 16, v54
	v_and_b32_e32 v53, 0xffff0000, v54
	v_pk_add_f32 v[134:135], v[52:53], 0 op_sel_hi:[1,0]
	v_add_co_u32_e32 v52, vcc, s47, v2
	v_lshlrev_b32_e32 v54, 16, v55
	v_and_b32_e32 v55, 0xffff0000, v55
	v_addc_co_u32_e32 v53, vcc, 0, v3, vcc
	v_pk_add_f32 v[136:137], v[54:55], 0 op_sel_hi:[1,0]
	v_mov_b32_e32 v52, v144
	v_mov_b32_e32 v53, v145
	v_mov_b32_e32 v54, v146
	v_mov_b32_e32 v55, v147
	v_pk_add_f32 v[128:129], v[128:129], 0 op_sel_hi:[1,0]
	s_waitcnt vmcnt(0)
	v_lshlrev_b32_e32 v138, 16, v52
	v_and_b32_e32 v139, 0xffff0000, v52
	v_lshlrev_b32_e32 v52, 16, v53
	v_and_b32_e32 v53, 0xffff0000, v53
	v_pk_add_f32 v[130:131], v[130:131], v[52:53]
	v_lshlrev_b32_e32 v52, 16, v54
	v_and_b32_e32 v53, 0xffff0000, v54
	v_pk_add_f32 v[134:135], v[134:135], v[52:53]
	v_add_co_u32_e32 v52, vcc, s68, v2
	v_lshlrev_b32_e32 v54, 16, v55
	v_and_b32_e32 v55, 0xffff0000, v55
	v_addc_co_u32_e32 v53, vcc, 0, v3, vcc
	v_pk_add_f32 v[136:137], v[136:137], v[54:55]
	v_mov_b32_e32 v52, v148
	v_mov_b32_e32 v53, v149
	v_mov_b32_e32 v54, v150
	v_mov_b32_e32 v55, v151
	v_pk_add_f32 v[128:129], v[128:129], v[138:139]
	s_waitcnt vmcnt(0)
	v_lshlrev_b32_e32 v138, 16, v52
	v_and_b32_e32 v139, 0xffff0000, v52
	v_lshlrev_b32_e32 v52, 16, v53
	v_and_b32_e32 v53, 0xffff0000, v53
	v_pk_add_f32 v[130:131], v[130:131], v[52:53]
	v_lshlrev_b32_e32 v52, 16, v54
	v_and_b32_e32 v53, 0xffff0000, v54
	v_pk_add_f32 v[134:135], v[134:135], v[52:53]
	v_add_co_u32_e32 v52, vcc, s48, v2
	v_lshlrev_b32_e32 v54, 16, v55
	v_and_b32_e32 v55, 0xffff0000, v55
	v_addc_co_u32_e32 v53, vcc, 0, v3, vcc
	v_pk_add_f32 v[136:137], v[136:137], v[54:55]
	v_mov_b32_e32 v52, v152
	v_mov_b32_e32 v53, v153
	v_mov_b32_e32 v54, v154
	v_mov_b32_e32 v55, v155
	v_pk_add_f32 v[128:129], v[128:129], v[138:139]
	v_add_co_u32_e32 v2, vcc, s49, v2
	s_waitcnt vmcnt(0)
	v_lshlrev_b32_e32 v138, 16, v52
	v_and_b32_e32 v139, 0xffff0000, v52
	v_lshlrev_b32_e32 v52, 16, v53
	v_and_b32_e32 v53, 0xffff0000, v53
	v_pk_add_f32 v[130:131], v[130:131], v[52:53]
	v_lshlrev_b32_e32 v52, 16, v54
	v_and_b32_e32 v53, 0xffff0000, v54
	v_lshlrev_b32_e32 v54, 16, v55
	v_and_b32_e32 v55, 0xffff0000, v55
	v_addc_co_u32_e32 v3, vcc, 0, v3, vcc
	v_pk_add_f32 v[136:137], v[136:137], v[54:55]
	v_pk_add_f32 v[134:135], v[134:135], v[52:53]
	v_mov_b32_e32 v52, v156
	v_mov_b32_e32 v53, v157
	v_mov_b32_e32 v54, v158
	v_mov_b32_e32 v55, v159
	v_pk_add_f32 v[128:129], v[128:129], v[138:139]
	s_waitcnt vmcnt(0)
	v_lshlrev_b32_e32 v2, 16, v52
	v_and_b32_e32 v3, 0xffff0000, v52
	v_lshlrev_b32_e32 v52, 16, v53
	v_and_b32_e32 v53, 0xffff0000, v53
	v_pk_add_f32 v[140:141], v[130:131], v[52:53]
	v_lshlrev_b32_e32 v52, 16, v55
	v_and_b32_e32 v53, 0xffff0000, v55
	v_pk_add_f32 v[138:139], v[128:129], v[2:3]
	v_lshlrev_b32_e32 v2, 16, v54
	v_and_b32_e32 v3, 0xffff0000, v54
	v_pk_add_f32 v[130:131], v[136:137], v[52:53]
	v_mov_b32_e32 v52, v160
	v_mov_b32_e32 v53, v161
	v_mov_b32_e32 v54, v162
	v_mov_b32_e32 v55, v163
	v_pk_add_f32 v[128:129], v[134:135], v[2:3]
	v_lshlrev_b64 v[2:3], 11, v[120:121]
	s_waitcnt vmcnt(0)
	v_pk_fma_f32 v[50:51], v[140:141], v[54:55], v[50:51]
	v_pk_fma_f32 v[48:49], v[138:139], v[52:53], v[48:49]
	v_mov_b32_e32 v52, v164
	v_mov_b32_e32 v53, v165
	v_mov_b32_e32 v54, v166
	v_mov_b32_e32 v55, v167
	s_waitcnt vmcnt(0)
; __device__ __forceinline__ unsigned pk_bf16(float lo, float hi) { unsigned r; asm volatile("v_cvt_pk_bf16_f32 %0, %1, %2" : "=v"(r) : "v"(lo), "v"(hi)); return r; }
; __device__ __forceinline__ float bflo(unsigned w) { return __uint_as_float(w << 16); }
; __device__ __forceinline__ float bfhi(unsigned w) { return __uint_as_float(w & 0xffff0000u); }
; __device__ __forceinline__ void phase_norm(int wv, const Params& p, int l, int which, int nrows, int nparts, const float* rgate) {
;     ...
;                     for (int jj = 0; jj < 2; ++jj) { f32x4 s0 = (f32x4){0.f, 0.f, 0.f, 0.f}, s1 = s0;
;                         for (int pt = 0; pt < nparts; ++pt) { const u32x4 w = *(const u32x4*)((const bf16_t*)(p.ws + OFF_S) + (size_t)pt * 2048 * 1024 + (size_t)(row - MLAT) * 1024 + jj * 512 + lane * 8);
;                             s0 += (f32x4){bflo(w.x), bfhi(w.x), bflo(w.y), bfhi(w.y)}; s1 += (f32x4){bflo(w.z), bfhi(w.z), bflo(w.w), bfhi(w.w)}; }
;                         v[u][2 * jj] += *(const f32x4*)(rgate + cq[2 * jj]) * s0; v[u][2 * jj + 1] += *(const f32x4*)(rgate + cq[2 * jj + 1]) * s1;
;                         u32x4 w; w.x = pk_bf16(v[u][2 * jj][0], v[u][2 * jj][1]); w.y = pk_bf16(v[u][2 * jj][2], v[u][2 * jj][3]); w.z = pk_bf16(v[u][2 * jj + 1][0], v[u][2 * jj + 1][1]); w.w = pk_bf16(v[u][2 * jj + 1][2], v[u][2 * jj + 1][3]);
;                         *(u32x4*)((bf16_t*)(p.ws + OFF_XB) + (size_t)row * 1024 + jj * 512 + lane * 8) = w; } }
	v_pk_fma_f32 v[44:45], v[128:129], v[52:53], v[44:45]
	v_cvt_pk_bf16_f32 v52, v48, v49
	v_cvt_pk_bf16_f32 v53, v50, v51
	v_lshl_add_u64 v[128:129], v[68:69], 0, v[2:3]
	v_pk_fma_f32 v[46:47], v[130:131], v[54:55], v[46:47]
	v_cvt_pk_bf16_f32 v54, v44, v45
	s_nop 0
	v_cvt_pk_bf16_f32 v55, v46, v47
	global_store_dwordx4 v[128:129], v[52:55], off
	s_nop 1
	v_lshl_add_u64 v[52:53], s[20:21], 0, v[126:127]
	v_lshl_add_u64 v[52:53], v[52:53], 0, v[0:1]
	v_add_co_u32_e32 v54, vcc, s50, v52
	s_nop 1
	v_addc_co_u32_e32 v55, vcc, 0, v53, vcc
	global_load_dwordx4 v[126:129], v[54:55], off offset:1024
	v_add_co_u32_e32 v168, vcc, s51, v52
	s_nop 1
	v_addc_co_u32_e32 v169, vcc, 0, v53, vcc
	global_load_dwordx4 v[144:147], v[168:169], off offset:1024
	v_add_co_u32_e32 v168, vcc, s52, v52
	s_nop 1
	v_addc_co_u32_e32 v169, vcc, 0, v53, vcc
	global_load_dwordx4 v[148:151], v[168:169], off offset:1024
	v_add_co_u32_e32 v168, vcc, s53, v52
	s_nop 1
	v_addc_co_u32_e32 v169, vcc, 0, v53, vcc
	global_load_dwordx4 v[152:155], v[168:169], off offset:1024
	v_add_co_u32_e32 v168, vcc, s56, v52
	s_nop 1
	v_addc_co_u32_e32 v169, vcc, 0, v53, vcc
	global_load_dwordx4 v[156:159], v[168:169], off offset:1024
	global_load_dwordx4 v[160:163], v[76:77], off
	global_load_dwordx4 v[164:167], v[78:79], off
	s_waitcnt vmcnt(0)
	v_lshlrev_b32_e32 v54, 16, v126
	v_and_b32_e32 v55, 0xffff0000, v126
	v_lshlrev_b32_e32 v126, 16, v127
	v_and_b32_e32 v127, 0xffff0000, v127
	v_pk_add_f32 v[130:131], v[126:127], 0 op_sel_hi:[1,0]
	v_lshlrev_b32_e32 v126, 16, v128
	v_and_b32_e32 v127, 0xffff0000, v128
	v_pk_add_f32 v[134:135], v[126:127], 0 op_sel_hi:[1,0]
	v_add_co_u32_e32 v126, vcc, s51, v52
	v_lshlrev_b32_e32 v128, 16, v129
	v_and_b32_e32 v129, 0xffff0000, v129
	v_addc_co_u32_e32 v127, vcc, 0, v53, vcc
	v_pk_add_f32 v[136:137], v[128:129], 0 op_sel_hi:[1,0]
	v_mov_b32_e32 v126, v144
	v_mov_b32_e32 v127, v145
	v_mov_b32_e32 v128, v146
	v_mov_b32_e32 v129, v147
	v_pk_add_f32 v[54:55], v[54:55], 0 op_sel_hi:[1,0]
	s_waitcnt vmcnt(0)
	v_lshlrev_b32_e32 v138, 16, v126
	v_and_b32_e32 v139, 0xffff0000, v126
	v_lshlrev_b32_e32 v126, 16, v127
	v_and_b32_e32 v127, 0xffff0000, v127
	v_pk_add_f32 v[130:131], v[130:131], v[126:127]
	v_lshlrev_b32_e32 v126, 16, v128
	v_and_b32_e32 v127, 0xffff0000, v128
	v_pk_add_f32 v[134:135], v[134:135], v[126:127]
	v_add_co_u32_e32 v126, vcc, s52, v52
	v_lshlrev_b32_e32 v128, 16, v129
	v_and_b32_e32 v129, 0xffff0000, v129
	v_addc_co_u32_e32 v127, vcc, 0, v53, vcc
	v_pk_add_f32 v[136:137], v[136:137], v[128:129]
	v_mov_b32_e32 v126, v148
	v_mov_b32_e32 v127, v149
	v_mov_b32_e32 v128, v150
	v_mov_b32_e32 v129, v151
	v_pk_add_f32 v[54:55], v[54:55], v[138:139]
	s_waitcnt vmcnt(0)
	v_lshlrev_b32_e32 v138, 16, v126
	v_and_b32_e32 v139, 0xffff0000, v126
	v_lshlrev_b32_e32 v126, 16, v127
	v_and_b32_e32 v127, 0xffff0000, v127
	v_pk_add_f32 v[130:131], v[130:131], v[126:127]
	v_lshlrev_b32_e32 v126, 16, v128
	v_and_b32_e32 v127, 0xffff0000, v128
	v_pk_add_f32 v[134:135], v[134:135], v[126:127]
	v_add_co_u32_e32 v126, vcc, s53, v52
	v_lshlrev_b32_e32 v128, 16, v129
	v_and_b32_e32 v129, 0xffff0000, v129
	v_addc_co_u32_e32 v127, vcc, 0, v53, vcc
	v_pk_add_f32 v[136:137], v[136:137], v[128:129]
	v_mov_b32_e32 v126, v152
	v_mov_b32_e32 v127, v153
	v_mov_b32_e32 v128, v154
	v_mov_b32_e32 v129, v155
	v_pk_add_f32 v[54:55], v[54:55], v[138:139]
	v_add_co_u32_e32 v52, vcc, s56, v52
	s_waitcnt vmcnt(0)
	v_lshlrev_b32_e32 v138, 16, v126
	v_and_b32_e32 v139, 0xffff0000, v126
	v_lshlrev_b32_e32 v126, 16, v127
	v_and_b32_e32 v127, 0xffff0000, v127
	v_pk_add_f32 v[126:127], v[130:131], v[126:127]
	v_pk_add_f32 v[130:131], v[54:55], v[138:139]
	v_lshlrev_b32_e32 v54, 16, v128
	v_and_b32_e32 v55, 0xffff0000, v128
	v_addc_co_u32_e32 v53, vcc, 0, v53, vcc
	v_pk_add_f32 v[134:135], v[134:135], v[54:55]
	v_mov_b32_e32 v52, v156
	v_mov_b32_e32 v53, v157
	v_mov_b32_e32 v54, v158
	v_mov_b32_e32 v55, v159
	v_lshlrev_b32_e32 v128, 16, v129
	v_and_b32_e32 v129, 0xffff0000, v129
	v_pk_add_f32 v[128:129], v[136:137], v[128:129]
	s_waitcnt vmcnt(0)
	v_lshlrev_b32_e32 v136, 16, v52
	v_and_b32_e32 v137, 0xffff0000, v52
	v_lshlrev_b32_e32 v52, 16, v53
	v_and_b32_e32 v53, 0xffff0000, v53
	v_pk_add_f32 v[130:131], v[130:131], v[136:137]
	v_pk_add_f32 v[136:137], v[126:127], v[52:53]
	v_lshlrev_b32_e32 v52, 16, v54
	v_and_b32_e32 v53, 0xffff0000, v54
	v_lshlrev_b32_e32 v54, 16, v55
	v_and_b32_e32 v55, 0xffff0000, v55
	v_pk_add_f32 v[126:127], v[134:135], v[52:53]
	v_pk_add_f32 v[128:129], v[128:129], v[54:55]
	v_mov_b32_e32 v52, v160
	v_mov_b32_e32 v53, v161
	v_mov_b32_e32 v54, v162
	v_mov_b32_e32 v55, v163
	s_waitcnt vmcnt(0)
	v_pk_fma_f32 v[42:43], v[136:137], v[54:55], v[42:43]
	v_pk_fma_f32 v[40:41], v[130:131], v[52:53], v[40:41]
	v_mov_b32_e32 v52, v164
	v_mov_b32_e32 v53, v165
	v_mov_b32_e32 v54, v166
	v_mov_b32_e32 v55, v167
	s_waitcnt vmcnt(0)
	v_pk_fma_f32 v[36:37], v[126:127], v[52:53], v[36:37]
	v_lshl_add_u64 v[126:127], s[20:21], 0, v[2:3]
	v_lshl_add_u64 v[126:127], v[126:127], 0, v[0:1]
	v_add_co_u32_e32 v126, vcc, 0xc60c000, v126
	v_pk_fma_f32 v[38:39], v[128:129], v[54:55], v[38:39]
	s_nop 0
	v_addc_co_u32_e32 v127, vcc, 0, v127, vcc
	v_cvt_pk_bf16_f32 v52, v40, v41
	v_cvt_pk_bf16_f32 v53, v42, v43
	v_cvt_pk_bf16_f32 v54, v36, v37
	v_cvt_pk_bf16_f32 v55, v38, v39
	global_store_dwordx4 v[126:127], v[52:55], off offset:1024

; __device__ __forceinline__ unsigned pk_bf16(float lo, float hi) { unsigned r; asm volatile("v_cvt_pk_bf16_f32 %0, %1, %2" : "=v"(r) : "v"(lo), "v"(hi)); return r; }
; __device__ __forceinline__ float bflo(unsigned w) { return __uint_as_float(w << 16); }
; __device__ __forceinline__ float bfhi(unsigned w) { return __uint_as_float(w & 0xffff0000u); }
; __device__ __forceinline__ void phase_norm(int wv, const Params& p, int l, int which, int nrows, int nparts, const float* rgate) {
;     ...
;                 if (!lat && nparts > 0) {
; #pragma unroll
;                     for (int jj = 0; jj < 2; ++jj) { f32x4 s0 = (f32x4){0.f, 0.f, 0.f, 0.f}, s1 = s0;
;                         for (int pt = 0; pt < nparts; ++pt) { const u32x4 w = *(const u32x4*)((const bf16_t*)(p.ws + OFF_S) + (size_t)pt * 2048 * 1024 + (size_t)(row - MLAT) * 1024 + jj * 512 + lane * 8);
;                             s0 += (f32x4){bflo(w.x), bfhi(w.x), bflo(w.y), bfhi(w.y)}; s1 += (f32x4){bflo(w.z), bfhi(w.z), bflo(w.w), bfhi(w.w)}; }
;                         v[u][2 * jj] += *(const f32x4*)(rgate + cq[2 * jj]) * s0; v[u][2 * jj + 1] += *(const f32x4*)(rgate + cq[2 * jj + 1]) * s1;
;                         u32x4 w; w.x = pk_bf16(v[u][2 * jj][0], v[u][2 * jj][1]); w.y = pk_bf16(v[u][2 * jj][2], v[u][2 * jj][3]); w.z = pk_bf16(v[u][2 * jj + 1][0], v[u][2 * jj + 1][1]); w.w = pk_bf16(v[u][2 * jj + 1][2], v[u][2 * jj + 1][3]);
;                         *(u32x4*)((bf16_t*)(p.ws + OFF_XB) + (size_t)row * 1024 + jj * 512 + lane * 8) = w; } }
.LBB0_118:
	v_readlane_b32 s0, v255, 20
	v_cmp_lt_i32_e64 s[14:15], s46, v116
	v_readlane_b32 s1, v255, 21
	s_and_b64 s[0:1], s[14:15], s[0:1]
	s_xor_b64 s[0:1], s[0:1], -1
	s_and_saveexec_b64 s[4:5], s[0:1]
	s_xor_b64 s[4:5], exec, s[4:5]
	v_mov_b32_e32 v117, v1
	v_lshlrev_b64 v[2:3], 11, v[116:117]
	s_andn2_saveexec_b64 s[34:35], s[4:5]
	s_cbranch_execz .LBB0_122
	v_mov_b32_e32 v125, v1
	v_lshlrev_b64 v[124:125], 11, v[124:125]
	v_lshl_add_u64 v[2:3], v[94:95], 0, v[124:125]
	global_load_dwordx4 v[52:55], v[2:3], off
	v_add_co_u32_e32 v168, vcc, s47, v2
	s_nop 1
	v_addc_co_u32_e32 v169, vcc, 0, v3, vcc
	global_load_dwordx4 v[144:147], v[168:169], off
	v_add_co_u32_e32 v168, vcc, s68, v2
	s_nop 1
	v_addc_co_u32_e32 v169, vcc, 0, v3, vcc
	global_load_dwordx4 v[148:151], v[168:169], off
	v_add_co_u32_e32 v168, vcc, s48, v2
	s_nop 1
	v_addc_co_u32_e32 v169, vcc, 0, v3, vcc
	global_load_dwordx4 v[152:155], v[168:169], off
	v_add_co_u32_e32 v168, vcc, s49, v2
	s_nop 1
	v_addc_co_u32_e32 v169, vcc, 0, v3, vcc
	global_load_dwordx4 v[156:159], v[168:169], off
	global_load_dwordx4 v[160:163], v[72:73], off
	global_load_dwordx4 v[164:167], v[74:75], off
	v_mov_b32_e32 v117, v1
	v_lshlrev_b32_e32 v0, 1, v58
	s_waitcnt vmcnt(0)
	v_lshlrev_b32_e32 v126, 16, v52
	v_and_b32_e32 v127, 0xffff0000, v52
	v_lshlrev_b32_e32 v52, 16, v53
	v_and_b32_e32 v53, 0xffff0000, v53
	v_pk_add_f32 v[128:129], v[52:53], 0 op_sel_hi:[1,0]
	v_lshlrev_b32_e32 v52, 16, v54
	v_and_b32_e32 v53, 0xffff0000, v54
	v_pk_add_f32 v[130:131], v[52:53], 0 op_sel_hi:[1,0]
	v_add_co_u32_e32 v52, vcc, s47, v2
	v_lshlrev_b32_e32 v54, 16, v55
	v_and_b32_e32 v55, 0xffff0000, v55
	v_addc_co_u32_e32 v53, vcc, 0, v3, vcc
	v_pk_add_f32 v[134:135], v[54:55], 0 op_sel_hi:[1,0]
	v_mov_b32_e32 v52, v144
	v_mov_b32_e32 v53, v145
	v_mov_b32_e32 v54, v146
	v_mov_b32_e32 v55, v147
	v_pk_add_f32 v[126:127], v[126:127], 0 op_sel_hi:[1,0]
	s_waitcnt vmcnt(0)
	v_lshlrev_b32_e32 v136, 16, v52
	v_and_b32_e32 v137, 0xffff0000, v52
	v_lshlrev_b32_e32 v52, 16, v53
	v_and_b32_e32 v53, 0xffff0000, v53
	v_pk_add_f32 v[128:129], v[128:129], v[52:53]
	v_lshlrev_b32_e32 v52, 16, v54
	v_and_b32_e32 v53, 0xffff0000, v54
	v_pk_add_f32 v[130:131], v[130:131], v[52:53]
	v_add_co_u32_e32 v52, vcc, s68, v2
	v_lshlrev_b32_e32 v54, 16, v55
	v_and_b32_e32 v55, 0xffff0000, v55
	v_addc_co_u32_e32 v53, vcc, 0, v3, vcc
	v_pk_add_f32 v[134:135], v[134:135], v[54:55]
	v_mov_b32_e32 v52, v148
	v_mov_b32_e32 v53, v149
	v_mov_b32_e32 v54, v150
	v_mov_b32_e32 v55, v151
	v_pk_add_f32 v[126:127], v[126:127], v[136:137]
	s_waitcnt vmcnt(0)
	v_lshlrev_b32_e32 v136, 16, v52
	v_and_b32_e32 v137, 0xffff0000, v52
	v_lshlrev_b32_e32 v52, 16, v53
	v_and_b32_e32 v53, 0xffff0000, v53
	v_pk_add_f32 v[128:129], v[128:129], v[52:53]
	v_lshlrev_b32_e32 v52, 16, v54
	v_and_b32_e32 v53, 0xffff0000, v54
	v_pk_add_f32 v[130:131], v[130:131], v[52:53]
	v_add_co_u32_e32 v52, vcc, s48, v2
	v_lshlrev_b32_e32 v54, 16, v55
	v_and_b32_e32 v55, 0xffff0000, v55
	v_addc_co_u32_e32 v53, vcc, 0, v3, vcc
	v_pk_add_f32 v[134:135], v[134:135], v[54:55]
	v_mov_b32_e32 v52, v152
	v_mov_b32_e32 v53, v153
	v_mov_b32_e32 v54, v154
	v_mov_b32_e32 v55, v155
	v_pk_add_f32 v[126:127], v[126:127], v[136:137]
	v_add_co_u32_e32 v2, vcc, s49, v2
	s_waitcnt vmcnt(0)
	v_lshlrev_b32_e32 v136, 16, v52
	v_and_b32_e32 v137, 0xffff0000, v52
	v_lshlrev_b32_e32 v52, 16, v53
	v_and_b32_e32 v53, 0xffff0000, v53
	v_pk_add_f32 v[128:129], v[128:129], v[52:53]
	v_lshlrev_b32_e32 v52, 16, v54
	v_and_b32_e32 v53, 0xffff0000, v54
	v_lshlrev_b32_e32 v54, 16, v55
	v_and_b32_e32 v55, 0xffff0000, v55
	v_addc_co_u32_e32 v3, vcc, 0, v3, vcc
	v_pk_add_f32 v[134:135], v[134:135], v[54:55]
	v_pk_add_f32 v[130:131], v[130:131], v[52:53]
	v_mov_b32_e32 v52, v156
	v_mov_b32_e32 v53, v157
	v_mov_b32_e32 v54, v158
	v_mov_b32_e32 v55, v159
	v_pk_add_f32 v[126:127], v[126:127], v[136:137]
	s_waitcnt vmcnt(0)
	v_lshlrev_b32_e32 v2, 16, v52
	v_and_b32_e32 v3, 0xffff0000, v52
	v_lshlrev_b32_e32 v52, 16, v53
	v_and_b32_e32 v53, 0xffff0000, v53
	v_pk_add_f32 v[138:139], v[128:129], v[52:53]
	v_lshlrev_b32_e32 v52, 16, v55
	v_and_b32_e32 v53, 0xffff0000, v55
	v_pk_add_f32 v[136:137], v[126:127], v[2:3]
	v_lshlrev_b32_e32 v2, 16, v54
	v_and_b32_e32 v3, 0xffff0000, v54
	v_pk_add_f32 v[128:129], v[134:135], v[52:53]
	v_mov_b32_e32 v52, v160
	v_mov_b32_e32 v53, v161
	v_mov_b32_e32 v54, v162
	v_mov_b32_e32 v55, v163
	v_pk_add_f32 v[126:127], v[130:131], v[2:3]
	v_lshlrev_b64 v[2:3], 11, v[116:117]
	s_waitcnt vmcnt(0)
	v_pk_fma_f32 v[34:35], v[138:139], v[54:55], v[34:35]
	v_pk_fma_f32 v[32:33], v[136:137], v[52:53], v[32:33]
	v_mov_b32_e32 v52, v164
	v_mov_b32_e32 v53, v165
	v_mov_b32_e32 v54, v166
	v_mov_b32_e32 v55, v167
	s_waitcnt vmcnt(0)
; __device__ __forceinline__ unsigned pk_bf16(float lo, float hi) { unsigned r; asm volatile("v_cvt_pk_bf16_f32 %0, %1, %2" : "=v"(r) : "v"(lo), "v"(hi)); return r; }
; __device__ __forceinline__ float bflo(unsigned w) { return __uint_as_float(w << 16); }
; __device__ __forceinline__ float bfhi(unsigned w) { return __uint_as_float(w & 0xffff0000u); }
; __device__ __forceinline__ void phase_norm(int wv, const Params& p, int l, int which, int nrows, int nparts, const float* rgate) {
;     ...
;                     for (int jj = 0; jj < 2; ++jj) { f32x4 s0 = (f32x4){0.f, 0.f, 0.f, 0.f}, s1 = s0;
;                         for (int pt = 0; pt < nparts; ++pt) { const u32x4 w = *(const u32x4*)((const bf16_t*)(p.ws + OFF_S) + (size_t)pt * 2048 * 1024 + (size_t)(row - MLAT) * 1024 + jj * 512 + lane * 8);
;                             s0 += (f32x4){bflo(w.x), bfhi(w.x), bflo(w.y), bfhi(w.y)}; s1 += (f32x4){bflo(w.z), bfhi(w.z), bflo(w.w), bfhi(w.w)}; }
;                         v[u][2 * jj] += *(const f32x4*)(rgate + cq[2 * jj]) * s0; v[u][2 * jj + 1] += *(const f32x4*)(rgate + cq[2 * jj + 1]) * s1;
;                         u32x4 w; w.x = pk_bf16(v[u][2 * jj][0], v[u][2 * jj][1]); w.y = pk_bf16(v[u][2 * jj][2], v[u][2 * jj][3]); w.z = pk_bf16(v[u][2 * jj + 1][0], v[u][2 * jj + 1][1]); w.w = pk_bf16(v[u][2 * jj + 1][2], v[u][2 * jj + 1][3]);
;                         *(u32x4*)((bf16_t*)(p.ws + OFF_XB) + (size_t)row * 1024 + jj * 512 + lane * 8) = w; } }
	v_pk_fma_f32 v[28:29], v[126:127], v[52:53], v[28:29]
	v_cvt_pk_bf16_f32 v52, v32, v33
	v_cvt_pk_bf16_f32 v53, v34, v35
	v_lshl_add_u64 v[126:127], v[68:69], 0, v[2:3]
	v_pk_fma_f32 v[30:31], v[128:129], v[54:55], v[30:31]
	v_cvt_pk_bf16_f32 v54, v28, v29
	s_nop 0
	v_cvt_pk_bf16_f32 v55, v30, v31
	global_store_dwordx4 v[126:127], v[52:55], off
	s_nop 1
	v_lshl_add_u64 v[52:53], s[20:21], 0, v[124:125]
	v_lshl_add_u64 v[52:53], v[52:53], 0, v[0:1]
	v_add_co_u32_e32 v54, vcc, s50, v52
	s_nop 1
	v_addc_co_u32_e32 v55, vcc, 0, v53, vcc
	global_load_dwordx4 v[124:127], v[54:55], off offset:1024
	v_add_co_u32_e32 v168, vcc, s51, v52
	s_nop 1
	v_addc_co_u32_e32 v169, vcc, 0, v53, vcc
	global_load_dwordx4 v[144:147], v[168:169], off offset:1024
	v_add_co_u32_e32 v168, vcc, s52, v52
	s_nop 1
	v_addc_co_u32_e32 v169, vcc, 0, v53, vcc
	global_load_dwordx4 v[148:151], v[168:169], off offset:1024
	v_add_co_u32_e32 v168, vcc, s53, v52
	s_nop 1
	v_addc_co_u32_e32 v169, vcc, 0, v53, vcc
	global_load_dwordx4 v[152:155], v[168:169], off offset:1024
	v_add_co_u32_e32 v168, vcc, s56, v52
	s_nop 1
	v_addc_co_u32_e32 v169, vcc, 0, v53, vcc
	global_load_dwordx4 v[156:159], v[168:169], off offset:1024
	global_load_dwordx4 v[160:163], v[76:77], off
	global_load_dwordx4 v[164:167], v[78:79], off
	s_waitcnt vmcnt(0)
	v_lshlrev_b32_e32 v54, 16, v124
	v_and_b32_e32 v55, 0xffff0000, v124
	v_lshlrev_b32_e32 v124, 16, v125
	v_and_b32_e32 v125, 0xffff0000, v125
	v_pk_add_f32 v[128:129], v[124:125], 0 op_sel_hi:[1,0]
	v_lshlrev_b32_e32 v124, 16, v126
	v_and_b32_e32 v125, 0xffff0000, v126
	v_pk_add_f32 v[130:131], v[124:125], 0 op_sel_hi:[1,0]
	v_add_co_u32_e32 v124, vcc, s51, v52
	v_lshlrev_b32_e32 v126, 16, v127
	v_and_b32_e32 v127, 0xffff0000, v127
	v_addc_co_u32_e32 v125, vcc, 0, v53, vcc
	v_pk_add_f32 v[134:135], v[126:127], 0 op_sel_hi:[1,0]
	v_mov_b32_e32 v124, v144
	v_mov_b32_e32 v125, v145
	v_mov_b32_e32 v126, v146
	v_mov_b32_e32 v127, v147
	v_pk_add_f32 v[54:55], v[54:55], 0 op_sel_hi:[1,0]
	s_waitcnt vmcnt(0)
	v_lshlrev_b32_e32 v136, 16, v124
	v_and_b32_e32 v137, 0xffff0000, v124
	v_lshlrev_b32_e32 v124, 16, v125
	v_and_b32_e32 v125, 0xffff0000, v125
	v_pk_add_f32 v[128:129], v[128:129], v[124:125]
	v_lshlrev_b32_e32 v124, 16, v126
	v_and_b32_e32 v125, 0xffff0000, v126
	v_pk_add_f32 v[130:131], v[130:131], v[124:125]
	v_add_co_u32_e32 v124, vcc, s52, v52
	v_lshlrev_b32_e32 v126, 16, v127
	v_and_b32_e32 v127, 0xffff0000, v127
	v_addc_co_u32_e32 v125, vcc, 0, v53, vcc
	v_pk_add_f32 v[134:135], v[134:135], v[126:127]
	v_mov_b32_e32 v124, v148
	v_mov_b32_e32 v125, v149
	v_mov_b32_e32 v126, v150
	v_mov_b32_e32 v127, v151
	v_pk_add_f32 v[54:55], v[54:55], v[136:137]
	s_waitcnt vmcnt(0)
	v_lshlrev_b32_e32 v136, 16, v124
	v_and_b32_e32 v137, 0xffff0000, v124
	v_lshlrev_b32_e32 v124, 16, v125
	v_and_b32_e32 v125, 0xffff0000, v125
	v_pk_add_f32 v[128:129], v[128:129], v[124:125]
	v_lshlrev_b32_e32 v124, 16, v126
	v_and_b32_e32 v125, 0xffff0000, v126
	v_pk_add_f32 v[130:131], v[130:131], v[124:125]
	v_add_co_u32_e32 v124, vcc, s53, v52
	v_lshlrev_b32_e32 v126, 16, v127
	v_and_b32_e32 v127, 0xffff0000, v127
	v_addc_co_u32_e32 v125, vcc, 0, v53, vcc
	v_pk_add_f32 v[134:135], v[134:135], v[126:127]
	v_mov_b32_e32 v124, v152
	v_mov_b32_e32 v125, v153
	v_mov_b32_e32 v126, v154
	v_mov_b32_e32 v127, v155
	v_pk_add_f32 v[54:55], v[54:55], v[136:137]
	v_add_co_u32_e32 v52, vcc, s56, v52
	s_waitcnt vmcnt(0)
	v_lshlrev_b32_e32 v136, 16, v124
	v_and_b32_e32 v137, 0xffff0000, v124
	v_lshlrev_b32_e32 v124, 16, v125
	v_and_b32_e32 v125, 0xffff0000, v125
	v_pk_add_f32 v[124:125], v[128:129], v[124:125]
	v_pk_add_f32 v[128:129], v[54:55], v[136:137]
	v_lshlrev_b32_e32 v54, 16, v126
	v_and_b32_e32 v55, 0xffff0000, v126
	v_addc_co_u32_e32 v53, vcc, 0, v53, vcc
	v_pk_add_f32 v[130:131], v[130:131], v[54:55]
	v_mov_b32_e32 v52, v156
	v_mov_b32_e32 v53, v157
	v_mov_b32_e32 v54, v158
	v_mov_b32_e32 v55, v159
	v_lshlrev_b32_e32 v126, 16, v127
	v_and_b32_e32 v127, 0xffff0000, v127
	v_pk_add_f32 v[126:127], v[134:135], v[126:127]
	s_waitcnt vmcnt(0)
	v_lshlrev_b32_e32 v134, 16, v52
	v_and_b32_e32 v135, 0xffff0000, v52
	v_lshlrev_b32_e32 v52, 16, v53
	v_and_b32_e32 v53, 0xffff0000, v53
	v_pk_add_f32 v[128:129], v[128:129], v[134:135]
	v_pk_add_f32 v[134:135], v[124:125], v[52:53]
	v_lshlrev_b32_e32 v52, 16, v54
	v_and_b32_e32 v53, 0xffff0000, v54
	v_lshlrev_b32_e32 v54, 16, v55
	v_and_b32_e32 v55, 0xffff0000, v55
	v_pk_add_f32 v[124:125], v[130:131], v[52:53]
	v_pk_add_f32 v[126:127], v[126:127], v[54:55]
	v_mov_b32_e32 v52, v160
	v_mov_b32_e32 v53, v161
	v_mov_b32_e32 v54, v162
	v_mov_b32_e32 v55, v163
	s_waitcnt vmcnt(0)
	v_pk_fma_f32 v[26:27], v[134:135], v[54:55], v[26:27]
	v_pk_fma_f32 v[24:25], v[128:129], v[52:53], v[24:25]
	v_mov_b32_e32 v52, v164
	v_mov_b32_e32 v53, v165
	v_mov_b32_e32 v54, v166
	v_mov_b32_e32 v55, v167
	s_waitcnt vmcnt(0)
	v_pk_fma_f32 v[20:21], v[124:125], v[52:53], v[20:21]
	v_lshl_add_u64 v[124:125], s[20:21], 0, v[2:3]
	v_lshl_add_u64 v[124:125], v[124:125], 0, v[0:1]
	v_add_co_u32_e32 v124, vcc, 0xc60c000, v124
	v_pk_fma_f32 v[22:23], v[126:127], v[54:55], v[22:23]
	s_nop 0
	v_addc_co_u32_e32 v125, vcc, 0, v125, vcc
	v_cvt_pk_bf16_f32 v52, v24, v25
	v_cvt_pk_bf16_f32 v53, v26, v27
	v_cvt_pk_bf16_f32 v54, v20, v21
	v_cvt_pk_bf16_f32 v55, v22, v23
	global_store_dwordx4 v[124:125], v[52:55], off offset:1024

; __device__ __forceinline__ unsigned pk_bf16(float lo, float hi) { unsigned r; asm volatile("v_cvt_pk_bf16_f32 %0, %1, %2" : "=v"(r) : "v"(lo), "v"(hi)); return r; }
; __device__ __forceinline__ float bflo(unsigned w) { return __uint_as_float(w << 16); }
; __device__ __forceinline__ float bfhi(unsigned w) { return __uint_as_float(w & 0xffff0000u); }
; __device__ __forceinline__ void phase_norm(int wv, const Params& p, int l, int which, int nrows, int nparts, const float* rgate) {
;     ...
;                 if (!lat && nparts > 0) {
; #pragma unroll
;                     for (int jj = 0; jj < 2; ++jj) { f32x4 s0 = (f32x4){0.f, 0.f, 0.f, 0.f}, s1 = s0;
;                         for (int pt = 0; pt < nparts; ++pt) { const u32x4 w = *(const u32x4*)((const bf16_t*)(p.ws + OFF_S) + (size_t)pt * 2048 * 1024 + (size_t)(row - MLAT) * 1024 + jj * 512 + lane * 8);
;                             s0 += (f32x4){bflo(w.x), bfhi(w.x), bflo(w.y), bfhi(w.y)}; s1 += (f32x4){bflo(w.z), bfhi(w.z), bflo(w.w), bfhi(w.w)}; }
;                         v[u][2 * jj] += *(const f32x4*)(rgate + cq[2 * jj]) * s0; v[u][2 * jj + 1] += *(const f32x4*)(rgate + cq[2 * jj + 1]) * s1;
;                         u32x4 w; w.x = pk_bf16(v[u][2 * jj][0], v[u][2 * jj][1]); w.y = pk_bf16(v[u][2 * jj][2], v[u][2 * jj][3]); w.z = pk_bf16(v[u][2 * jj + 1][0], v[u][2 * jj + 1][1]); w.w = pk_bf16(v[u][2 * jj + 1][2], v[u][2 * jj + 1][3]);
;                         *(u32x4*)((bf16_t*)(p.ws + OFF_XB) + (size_t)row * 1024 + jj * 512 + lane * 8) = w; } }
.LBB0_131:
	v_readlane_b32 s0, v255, 20
	v_cmp_lt_i32_e64 s[14:15], s46, v114
	v_readlane_b32 s1, v255, 21
	s_and_b64 s[0:1], s[14:15], s[0:1]
	s_xor_b64 s[0:1], s[0:1], -1
	s_and_saveexec_b64 s[4:5], s[0:1]
	s_xor_b64 s[4:5], exec, s[4:5]
	v_mov_b32_e32 v115, v1
	v_lshlrev_b64 v[2:3], 11, v[114:115]
	s_andn2_saveexec_b64 s[34:35], s[4:5]
	s_cbranch_execz .LBB0_135
	v_mov_b32_e32 v123, v1
	v_lshlrev_b64 v[122:123], 11, v[122:123]
	v_lshl_add_u64 v[2:3], v[94:95], 0, v[122:123]
	global_load_dwordx4 v[52:55], v[2:3], off
	v_add_co_u32_e32 v168, vcc, s47, v2
	s_nop 1
	v_addc_co_u32_e32 v169, vcc, 0, v3, vcc
	global_load_dwordx4 v[144:147], v[168:169], off
	v_add_co_u32_e32 v168, vcc, s68, v2
	s_nop 1
	v_addc_co_u32_e32 v169, vcc, 0, v3, vcc
	global_load_dwordx4 v[148:151], v[168:169], off
	v_add_co_u32_e32 v168, vcc, s48, v2
	s_nop 1
	v_addc_co_u32_e32 v169, vcc, 0, v3, vcc
	global_load_dwordx4 v[152:155], v[168:169], off
	v_add_co_u32_e32 v168, vcc, s49, v2
	s_nop 1
	v_addc_co_u32_e32 v169, vcc, 0, v3, vcc
	global_load_dwordx4 v[156:159], v[168:169], off
	global_load_dwordx4 v[160:163], v[72:73], off
	global_load_dwordx4 v[164:167], v[74:75], off
	v_mov_b32_e32 v115, v1
	v_lshlrev_b32_e32 v0, 1, v58
	s_waitcnt vmcnt(0)
	v_lshlrev_b32_e32 v124, 16, v52
	v_and_b32_e32 v125, 0xffff0000, v52
	v_lshlrev_b32_e32 v52, 16, v53
	v_and_b32_e32 v53, 0xffff0000, v53
	v_pk_add_f32 v[126:127], v[52:53], 0 op_sel_hi:[1,0]
	v_lshlrev_b32_e32 v52, 16, v54
	v_and_b32_e32 v53, 0xffff0000, v54
	v_pk_add_f32 v[128:129], v[52:53], 0 op_sel_hi:[1,0]
	v_add_co_u32_e32 v52, vcc, s47, v2
	v_lshlrev_b32_e32 v54, 16, v55
	v_and_b32_e32 v55, 0xffff0000, v55
	v_addc_co_u32_e32 v53, vcc, 0, v3, vcc
	v_pk_add_f32 v[130:131], v[54:55], 0 op_sel_hi:[1,0]
	v_mov_b32_e32 v52, v144
	v_mov_b32_e32 v53, v145
	v_mov_b32_e32 v54, v146
	v_mov_b32_e32 v55, v147
	v_pk_add_f32 v[124:125], v[124:125], 0 op_sel_hi:[1,0]
	s_waitcnt vmcnt(0)
	v_lshlrev_b32_e32 v134, 16, v52
	v_and_b32_e32 v135, 0xffff0000, v52
	v_lshlrev_b32_e32 v52, 16, v53
	v_and_b32_e32 v53, 0xffff0000, v53
	v_pk_add_f32 v[126:127], v[126:127], v[52:53]
	v_lshlrev_b32_e32 v52, 16, v54
	v_and_b32_e32 v53, 0xffff0000, v54
	v_pk_add_f32 v[128:129], v[128:129], v[52:53]
	v_add_co_u32_e32 v52, vcc, s68, v2
	v_lshlrev_b32_e32 v54, 16, v55
	v_and_b32_e32 v55, 0xffff0000, v55
	v_addc_co_u32_e32 v53, vcc, 0, v3, vcc
	v_pk_add_f32 v[130:131], v[130:131], v[54:55]
	v_mov_b32_e32 v52, v148
	v_mov_b32_e32 v53, v149
	v_mov_b32_e32 v54, v150
	v_mov_b32_e32 v55, v151
	v_pk_add_f32 v[124:125], v[124:125], v[134:135]
	s_waitcnt vmcnt(0)
	v_lshlrev_b32_e32 v134, 16, v52
	v_and_b32_e32 v135, 0xffff0000, v52
	v_lshlrev_b32_e32 v52, 16, v53
	v_and_b32_e32 v53, 0xffff0000, v53
	v_pk_add_f32 v[126:127], v[126:127], v[52:53]
	v_lshlrev_b32_e32 v52, 16, v54
	v_and_b32_e32 v53, 0xffff0000, v54
	v_pk_add_f32 v[128:129], v[128:129], v[52:53]
	v_add_co_u32_e32 v52, vcc, s48, v2
	v_lshlrev_b32_e32 v54, 16, v55
	v_and_b32_e32 v55, 0xffff0000, v55
	v_addc_co_u32_e32 v53, vcc, 0, v3, vcc
	v_pk_add_f32 v[130:131], v[130:131], v[54:55]
	v_mov_b32_e32 v52, v152
	v_mov_b32_e32 v53, v153
	v_mov_b32_e32 v54, v154
	v_mov_b32_e32 v55, v155
	v_pk_add_f32 v[124:125], v[124:125], v[134:135]
	v_add_co_u32_e32 v2, vcc, s49, v2
	s_waitcnt vmcnt(0)
	v_lshlrev_b32_e32 v134, 16, v52
	v_and_b32_e32 v135, 0xffff0000, v52
	v_lshlrev_b32_e32 v52, 16, v53
	v_and_b32_e32 v53, 0xffff0000, v53
	v_pk_add_f32 v[126:127], v[126:127], v[52:53]
	v_lshlrev_b32_e32 v52, 16, v54
	v_and_b32_e32 v53, 0xffff0000, v54
	v_lshlrev_b32_e32 v54, 16, v55
	v_and_b32_e32 v55, 0xffff0000, v55
	v_addc_co_u32_e32 v3, vcc, 0, v3, vcc
	v_pk_add_f32 v[130:131], v[130:131], v[54:55]
	v_pk_add_f32 v[128:129], v[128:129], v[52:53]
	v_mov_b32_e32 v52, v156
	v_mov_b32_e32 v53, v157
	v_mov_b32_e32 v54, v158
	v_mov_b32_e32 v55, v159
	v_pk_add_f32 v[124:125], v[124:125], v[134:135]
	s_waitcnt vmcnt(0)
	v_lshlrev_b32_e32 v2, 16, v52
	v_and_b32_e32 v3, 0xffff0000, v52
	v_lshlrev_b32_e32 v52, 16, v53
	v_and_b32_e32 v53, 0xffff0000, v53
	v_pk_add_f32 v[136:137], v[126:127], v[52:53]
	v_lshlrev_b32_e32 v52, 16, v55
	v_and_b32_e32 v53, 0xffff0000, v55
	v_pk_add_f32 v[134:135], v[124:125], v[2:3]
	v_lshlrev_b32_e32 v2, 16, v54
	v_and_b32_e32 v3, 0xffff0000, v54
	v_pk_add_f32 v[126:127], v[130:131], v[52:53]
	v_mov_b32_e32 v52, v160
	v_mov_b32_e32 v53, v161
	v_mov_b32_e32 v54, v162
	v_mov_b32_e32 v55, v163
	v_pk_add_f32 v[124:125], v[128:129], v[2:3]
	v_lshlrev_b64 v[2:3], 11, v[114:115]
	s_waitcnt vmcnt(0)
	v_pk_fma_f32 v[18:19], v[136:137], v[54:55], v[18:19]
	v_pk_fma_f32 v[16:17], v[134:135], v[52:53], v[16:17]
	v_mov_b32_e32 v52, v164
	v_mov_b32_e32 v53, v165
	v_mov_b32_e32 v54, v166
	v_mov_b32_e32 v55, v167
	s_waitcnt vmcnt(0)
; __device__ __forceinline__ unsigned pk_bf16(float lo, float hi) { unsigned r; asm volatile("v_cvt_pk_bf16_f32 %0, %1, %2" : "=v"(r) : "v"(lo), "v"(hi)); return r; }
; __device__ __forceinline__ float bflo(unsigned w) { return __uint_as_float(w << 16); }
; __device__ __forceinline__ float bfhi(unsigned w) { return __uint_as_float(w & 0xffff0000u); }
; __device__ __forceinline__ void phase_norm(int wv, const Params& p, int l, int which, int nrows, int nparts, const float* rgate) {
;     ...
;                     for (int jj = 0; jj < 2; ++jj) { f32x4 s0 = (f32x4){0.f, 0.f, 0.f, 0.f}, s1 = s0;
;                         for (int pt = 0; pt < nparts; ++pt) { const u32x4 w = *(const u32x4*)((const bf16_t*)(p.ws + OFF_S) + (size_t)pt * 2048 * 1024 + (size_t)(row - MLAT) * 1024 + jj * 512 + lane * 8);
;                             s0 += (f32x4){bflo(w.x), bfhi(w.x), bflo(w.y), bfhi(w.y)}; s1 += (f32x4){bflo(w.z), bfhi(w.z), bflo(w.w), bfhi(w.w)}; }
;                         v[u][2 * jj] += *(const f32x4*)(rgate + cq[2 * jj]) * s0; v[u][2 * jj + 1] += *(const f32x4*)(rgate + cq[2 * jj + 1]) * s1;
;                         u32x4 w; w.x = pk_bf16(v[u][2 * jj][0], v[u][2 * jj][1]); w.y = pk_bf16(v[u][2 * jj][2], v[u][2 * jj][3]); w.z = pk_bf16(v[u][2 * jj + 1][0], v[u][2 * jj + 1][1]); w.w = pk_bf16(v[u][2 * jj + 1][2], v[u][2 * jj + 1][3]);
;                         *(u32x4*)((bf16_t*)(p.ws + OFF_XB) + (size_t)row * 1024 + jj * 512 + lane * 8) = w; } }
	v_pk_fma_f32 v[12:13], v[124:125], v[52:53], v[12:13]
	v_cvt_pk_bf16_f32 v52, v16, v17
	v_cvt_pk_bf16_f32 v53, v18, v19
	v_lshl_add_u64 v[124:125], v[68:69], 0, v[2:3]
	v_pk_fma_f32 v[14:15], v[126:127], v[54:55], v[14:15]
	v_cvt_pk_bf16_f32 v54, v12, v13
	s_nop 0
	v_cvt_pk_bf16_f32 v55, v14, v15
	global_store_dwordx4 v[124:125], v[52:55], off
	s_nop 1
	v_lshl_add_u64 v[52:53], s[20:21], 0, v[122:123]
	v_lshl_add_u64 v[52:53], v[52:53], 0, v[0:1]
	v_add_co_u32_e32 v54, vcc, s50, v52
	s_nop 1
	v_addc_co_u32_e32 v55, vcc, 0, v53, vcc
	global_load_dwordx4 v[122:125], v[54:55], off offset:1024
	v_add_co_u32_e32 v168, vcc, s51, v52
	s_nop 1
	v_addc_co_u32_e32 v169, vcc, 0, v53, vcc
	global_load_dwordx4 v[144:147], v[168:169], off offset:1024
	v_add_co_u32_e32 v168, vcc, s52, v52
	s_nop 1
	v_addc_co_u32_e32 v169, vcc, 0, v53, vcc
	global_load_dwordx4 v[148:151], v[168:169], off offset:1024
	v_add_co_u32_e32 v168, vcc, s53, v52
	s_nop 1
	v_addc_co_u32_e32 v169, vcc, 0, v53, vcc
	global_load_dwordx4 v[152:155], v[168:169], off offset:1024
	v_add_co_u32_e32 v168, vcc, s56, v52
	s_nop 1
	v_addc_co_u32_e32 v169, vcc, 0, v53, vcc
	global_load_dwordx4 v[156:159], v[168:169], off offset:1024
	global_load_dwordx4 v[160:163], v[76:77], off
	global_load_dwordx4 v[164:167], v[78:79], off
	s_waitcnt vmcnt(0)
	v_lshlrev_b32_e32 v54, 16, v122
	v_and_b32_e32 v55, 0xffff0000, v122
	v_lshlrev_b32_e32 v122, 16, v123
	v_and_b32_e32 v123, 0xffff0000, v123
	v_pk_add_f32 v[126:127], v[122:123], 0 op_sel_hi:[1,0]
	v_lshlrev_b32_e32 v122, 16, v124
	v_and_b32_e32 v123, 0xffff0000, v124
	v_pk_add_f32 v[128:129], v[122:123], 0 op_sel_hi:[1,0]
	v_add_co_u32_e32 v122, vcc, s51, v52
	v_lshlrev_b32_e32 v124, 16, v125
	v_and_b32_e32 v125, 0xffff0000, v125
	v_addc_co_u32_e32 v123, vcc, 0, v53, vcc
	v_pk_add_f32 v[130:131], v[124:125], 0 op_sel_hi:[1,0]
	v_mov_b32_e32 v122, v144
	v_mov_b32_e32 v123, v145
	v_mov_b32_e32 v124, v146
	v_mov_b32_e32 v125, v147
	v_pk_add_f32 v[54:55], v[54:55], 0 op_sel_hi:[1,0]
	s_waitcnt vmcnt(0)
	v_lshlrev_b32_e32 v134, 16, v122
	v_and_b32_e32 v135, 0xffff0000, v122
	v_lshlrev_b32_e32 v122, 16, v123
	v_and_b32_e32 v123, 0xffff0000, v123
	v_pk_add_f32 v[126:127], v[126:127], v[122:123]
	v_lshlrev_b32_e32 v122, 16, v124
	v_and_b32_e32 v123, 0xffff0000, v124
	v_pk_add_f32 v[128:129], v[128:129], v[122:123]
	v_add_co_u32_e32 v122, vcc, s52, v52
	v_lshlrev_b32_e32 v124, 16, v125
	v_and_b32_e32 v125, 0xffff0000, v125
	v_addc_co_u32_e32 v123, vcc, 0, v53, vcc
	v_pk_add_f32 v[130:131], v[130:131], v[124:125]
	v_mov_b32_e32 v122, v148
	v_mov_b32_e32 v123, v149
	v_mov_b32_e32 v124, v150
	v_mov_b32_e32 v125, v151
	v_pk_add_f32 v[54:55], v[54:55], v[134:135]
	s_waitcnt vmcnt(0)
	v_lshlrev_b32_e32 v134, 16, v122
	v_and_b32_e32 v135, 0xffff0000, v122
	v_lshlrev_b32_e32 v122, 16, v123
	v_and_b32_e32 v123, 0xffff0000, v123
	v_pk_add_f32 v[126:127], v[126:127], v[122:123]
	v_lshlrev_b32_e32 v122, 16, v124
	v_and_b32_e32 v123, 0xffff0000, v124
	v_pk_add_f32 v[128:129], v[128:129], v[122:123]
	v_add_co_u32_e32 v122, vcc, s53, v52
	v_lshlrev_b32_e32 v124, 16, v125
	v_and_b32_e32 v125, 0xffff0000, v125
	v_addc_co_u32_e32 v123, vcc, 0, v53, vcc
	v_pk_add_f32 v[130:131], v[130:131], v[124:125]
	v_mov_b32_e32 v122, v152
	v_mov_b32_e32 v123, v153
	v_mov_b32_e32 v124, v154
	v_mov_b32_e32 v125, v155
	v_pk_add_f32 v[54:55], v[54:55], v[134:135]
	v_add_co_u32_e32 v52, vcc, s56, v52
	s_waitcnt vmcnt(0)
	v_lshlrev_b32_e32 v134, 16, v122
	v_and_b32_e32 v135, 0xffff0000, v122
	v_lshlrev_b32_e32 v122, 16, v123
	v_and_b32_e32 v123, 0xffff0000, v123
	v_pk_add_f32 v[122:123], v[126:127], v[122:123]
	v_pk_add_f32 v[126:127], v[54:55], v[134:135]
	v_lshlrev_b32_e32 v54, 16, v124
	v_and_b32_e32 v55, 0xffff0000, v124
	v_addc_co_u32_e32 v53, vcc, 0, v53, vcc
	v_pk_add_f32 v[128:129], v[128:129], v[54:55]
	v_mov_b32_e32 v52, v156
	v_mov_b32_e32 v53, v157
	v_mov_b32_e32 v54, v158
	v_mov_b32_e32 v55, v159
	v_lshlrev_b32_e32 v124, 16, v125
	v_and_b32_e32 v125, 0xffff0000, v125
	v_pk_add_f32 v[124:125], v[130:131], v[124:125]
	s_waitcnt vmcnt(0)
	v_lshlrev_b32_e32 v130, 16, v52
	v_and_b32_e32 v131, 0xffff0000, v52
	v_lshlrev_b32_e32 v52, 16, v53
	v_and_b32_e32 v53, 0xffff0000, v53
	v_pk_add_f32 v[126:127], v[126:127], v[130:131]
	v_pk_add_f32 v[130:131], v[122:123], v[52:53]
	v_lshlrev_b32_e32 v52, 16, v54
	v_and_b32_e32 v53, 0xffff0000, v54
	v_lshlrev_b32_e32 v54, 16, v55
	v_and_b32_e32 v55, 0xffff0000, v55
	v_pk_add_f32 v[122:123], v[128:129], v[52:53]
	v_pk_add_f32 v[124:125], v[124:125], v[54:55]
	v_mov_b32_e32 v52, v160
	v_mov_b32_e32 v53, v161
	v_mov_b32_e32 v54, v162
	v_mov_b32_e32 v55, v163
	s_waitcnt vmcnt(0)
	v_pk_fma_f32 v[10:11], v[130:131], v[54:55], v[10:11]
	v_pk_fma_f32 v[8:9], v[126:127], v[52:53], v[8:9]
	v_mov_b32_e32 v52, v164
	v_mov_b32_e32 v53, v165
	v_mov_b32_e32 v54, v166
	v_mov_b32_e32 v55, v167
	s_waitcnt vmcnt(0)
	v_pk_fma_f32 v[4:5], v[122:123], v[52:53], v[4:5]
	v_lshl_add_u64 v[122:123], s[20:21], 0, v[2:3]
	v_lshl_add_u64 v[122:123], v[122:123], 0, v[0:1]
	v_add_co_u32_e32 v122, vcc, 0xc60c000, v122
	v_pk_fma_f32 v[6:7], v[124:125], v[54:55], v[6:7]
	s_nop 0
	v_addc_co_u32_e32 v123, vcc, 0, v123, vcc
	v_cvt_pk_bf16_f32 v52, v8, v9
	v_cvt_pk_bf16_f32 v53, v10, v11
	v_cvt_pk_bf16_f32 v54, v4, v5
	v_cvt_pk_bf16_f32 v55, v6, v7
	global_store_dwordx4 v[122:123], v[52:55], off offset:1024

; __device__ __forceinline__ unsigned pk_bf16(float lo, float hi) { unsigned r; asm volatile("v_cvt_pk_bf16_f32 %0, %1, %2" : "=v"(r) : "v"(lo), "v"(hi)); return r; }
; __device__ __forceinline__ float bflo(unsigned w) { return __uint_as_float(w << 16); }
; __device__ __forceinline__ float bfhi(unsigned w) { return __uint_as_float(w & 0xffff0000u); }
; __device__ __forceinline__ int otid(int wv) { int ln; asm volatile("v_mbcnt_lo_u32_b32 %0, -1, 0\n\tv_mbcnt_hi_u32_b32 %0, -1, %0" : "=v"(ln)); return wv * 64 + ln; }
; __device__ __forceinline__ void gla_scan(int wv, const Params& p) {
;     bf16_t* S = (bf16_t*)(p.ws + OFF_S); const float* DEC = (const float*)(p.ws + OFF_DEC);
;     for (int e = blockIdx.x * 512 + otid(wv); e < 147456; e += gridDim.x * 512) {
;         const int chain = e / 2304, idx = (e % 2304) * 2, dk = idx % 48, dir = chain & 1; const size_t base = (size_t)chain * 36;
;         float s0 = 0.f, s1 = 0.f;
;         for (int st0 = 0; st0 < 36; st0 += 6) { unsigned v[6]; float d0[6], d1[6]; unsigned* sp[6];
; #pragma unroll
;             for (int u = 0; u < 6; ++u) { const int st = st0 + u, n = dir ? 35 - st : (st < 4 ? 32 + st : st - 4); sp[u] = (unsigned*)(S + (base + n) * 4608 + idx); v[u] = *sp[u];
;                 const float* dp = DEC + (base + n) * 48 + dk; d0[u] = dp[0]; d1[u] = dp[1]; }
; #pragma unroll
;             for (int u = 0; u < 6; ++u) { *sp[u] = pk_bf16(s0, s1); s0 = s0 * d0[u] + bflo(v[u]); s1 = s1 * d1[u] + bfhi(v[u]); } }
.LBB0_884:
	v_readfirstlane_b32 s0, v0
	s_lshr_b32 s3, s0, 8
	s_mul_hi_u32 s3, s3, 0x38e38e39
	s_lshr_b32 s3, s3, 1
	s_mul_i32 s1, s3, 0x900
	s_sub_u32 s1, s0, s1
	v_subrev_u32_e32 v2, s0, v0
	v_add_u32_e32 v2, s1, v2
	v_lshrrev_b32_e32 v3, 3, v2
	s_mov_b32 s1, 0x55555556
	v_mul_hi_u32 v3, v3, s1
	v_mul_u32_u24_e32 v3, 24, v3
	v_sub_u32_e32 v3, v2, v3
	v_lshlrev_b32_e32 v3, 3, v3
	v_lshlrev_b32_e32 v2, 2, v2
	s_mul_i32 s1, s3, 0x51000
	s_add_u32 s14, s8, s1
	s_addc_u32 s15, s9, 0
	s_mul_i32 s1, s3, 0x1b00
	s_add_u32 s4, s10, s1
	s_addc_u32 s5, s11, 0
	v_mov_b32_e32 v6, 0
	v_mov_b32_e32 v7, 0
	s_bitcmp1_b32 s3, 0
	s_cbranch_scc1 .Lscan_dir1
	s_add_u32 s0, s4, 0x1800
	s_addc_u32 s1, s5, 0
	global_load_dwordx2 v[10:11], v3, s[0:1]
	s_add_u32 s0, s14, 0x48000
	s_addc_u32 s1, s15, 0
	global_load_dword v82, v2, s[0:1]
	s_add_u32 s0, s4, 0x18c0
	s_addc_u32 s1, s5, 0
	global_load_dwordx2 v[12:13], v3, s[0:1]
	s_add_u32 s0, s14, 0x4a400
	s_addc_u32 s1, s15, 0
	global_load_dword v83, v2, s[0:1]
	s_add_u32 s0, s4, 0x1980
	s_addc_u32 s1, s5, 0
	global_load_dwordx2 v[14:15], v3, s[0:1]
	s_add_u32 s0, s14, 0x4c800
	s_addc_u32 s1, s15, 0
	global_load_dword v84, v2, s[0:1]
	s_add_u32 s0, s4, 0x1a40
	s_addc_u32 s1, s5, 0
	global_load_dwordx2 v[16:17], v3, s[0:1]
	s_add_u32 s0, s14, 0x4ec00
	s_addc_u32 s1, s15, 0
	global_load_dword v85, v2, s[0:1]
	s_add_u32 s0, s4, 0x0
	s_addc_u32 s1, s5, 0
	global_load_dwordx2 v[18:19], v3, s[0:1]
	s_add_u32 s0, s14, 0x0
	s_addc_u32 s1, s15, 0
	global_load_dword v86, v2, s[0:1]
	s_add_u32 s0, s4, 0xc0
	s_addc_u32 s1, s5, 0
	global_load_dwordx2 v[20:21], v3, s[0:1]
	s_add_u32 s0, s14, 0x2400
	s_addc_u32 s1, s15, 0
	global_load_dword v87, v2, s[0:1]
	s_add_u32 s0, s4, 0x180
	s_addc_u32 s1, s5, 0
	global_load_dwordx2 v[22:23], v3, s[0:1]
	s_add_u32 s0, s14, 0x4800
	s_addc_u32 s1, s15, 0
	global_load_dword v88, v2, s[0:1]
	s_add_u32 s0, s4, 0x240
	s_addc_u32 s1, s5, 0
	global_load_dwordx2 v[24:25], v3, s[0:1]
	s_add_u32 s0, s14, 0x6c00
	s_addc_u32 s1, s15, 0
	global_load_dword v89, v2, s[0:1]
	s_add_u32 s0, s4, 0x300
	s_addc_u32 s1, s5, 0
	global_load_dwordx2 v[26:27], v3, s[0:1]
	s_add_u32 s0, s14, 0x9000
	s_addc_u32 s1, s15, 0
	global_load_dword v90, v2, s[0:1]
	s_add_u32 s0, s4, 0x3c0
	s_addc_u32 s1, s5, 0
	global_load_dwordx2 v[28:29], v3, s[0:1]
	s_add_u32 s0, s14, 0xb400
	s_addc_u32 s1, s15, 0
	global_load_dword v91, v2, s[0:1]
	s_add_u32 s0, s4, 0x480
	s_addc_u32 s1, s5, 0
	global_load_dwordx2 v[30:31], v3, s[0:1]
	s_add_u32 s0, s14, 0xd800
	s_addc_u32 s1, s15, 0
	global_load_dword v92, v2, s[0:1]
	s_add_u32 s0, s4, 0x540
	s_addc_u32 s1, s5, 0
	global_load_dwordx2 v[32:33], v3, s[0:1]
	s_add_u32 s0, s14, 0xfc00
	s_addc_u32 s1, s15, 0
	global_load_dword v93, v2, s[0:1]
	s_add_u32 s0, s4, 0x600
	s_addc_u32 s1, s5, 0
	global_load_dwordx2 v[34:35], v3, s[0:1]
	s_add_u32 s0, s14, 0x12000
	s_addc_u32 s1, s15, 0
	global_load_dword v94, v2, s[0:1]
	s_add_u32 s0, s4, 0x6c0
	s_addc_u32 s1, s5, 0
	global_load_dwordx2 v[36:37], v3, s[0:1]
	s_add_u32 s0, s14, 0x14400
	s_addc_u32 s1, s15, 0
	global_load_dword v95, v2, s[0:1]
	s_add_u32 s0, s4, 0x780
	s_addc_u32 s1, s5, 0
	global_load_dwordx2 v[38:39], v3, s[0:1]
	s_add_u32 s0, s14, 0x16800
	s_addc_u32 s1, s15, 0
	global_load_dword v96, v2, s[0:1]
	s_add_u32 s0, s4, 0x840
	s_addc_u32 s1, s5, 0
	global_load_dwordx2 v[40:41], v3, s[0:1]
	s_add_u32 s0, s14, 0x18c00
	s_addc_u32 s1, s15, 0
	global_load_dword v97, v2, s[0:1]
	s_add_u32 s0, s4, 0x900
	s_addc_u32 s1, s5, 0
	global_load_dwordx2 v[42:43], v3, s[0:1]
	s_add_u32 s0, s14, 0x1b000
	s_addc_u32 s1, s15, 0
	global_load_dword v98, v2, s[0:1]
	s_add_u32 s0, s4, 0x9c0
	s_addc_u32 s1, s5, 0
	global_load_dwordx2 v[44:45], v3, s[0:1]
	s_add_u32 s0, s14, 0x1d400
	s_addc_u32 s1, s15, 0
	global_load_dword v99, v2, s[0:1]
	s_add_u32 s0, s4, 0xa80
	s_addc_u32 s1, s5, 0
	global_load_dwordx2 v[46:47], v3, s[0:1]
	s_add_u32 s0, s14, 0x1f800
	s_addc_u32 s1, s15, 0
	global_load_dword v100, v2, s[0:1]
	s_add_u32 s0, s4, 0xb40
	s_addc_u32 s1, s5, 0
	global_load_dwordx2 v[48:49], v3, s[0:1]
	s_add_u32 s0, s14, 0x21c00
	s_addc_u32 s1, s15, 0
	global_load_dword v101, v2, s[0:1]
	s_add_u32 s0, s4, 0xc00
	s_addc_u32 s1, s5, 0
	global_load_dwordx2 v[50:51], v3, s[0:1]
	s_add_u32 s0, s14, 0x24000
	s_addc_u32 s1, s15, 0
	global_load_dword v102, v2, s[0:1]
	s_add_u32 s0, s4, 0xcc0
	s_addc_u32 s1, s5, 0
	global_load_dwordx2 v[52:53], v3, s[0:1]
	s_add_u32 s0, s14, 0x26400
	s_addc_u32 s1, s15, 0
	global_load_dword v103, v2, s[0:1]
	s_add_u32 s0, s4, 0xd80
	s_addc_u32 s1, s5, 0
	global_load_dwordx2 v[54:55], v3, s[0:1]
	s_add_u32 s0, s14, 0x28800
	s_addc_u32 s1, s15, 0
	global_load_dword v104, v2, s[0:1]
	s_add_u32 s0, s4, 0xe40
	s_addc_u32 s1, s5, 0
	global_load_dwordx2 v[56:57], v3, s[0:1]
	s_add_u32 s0, s14, 0x2ac00
	s_addc_u32 s1, s15, 0
	global_load_dword v105, v2, s[0:1]
	s_add_u32 s0, s4, 0xf00
	s_addc_u32 s1, s5, 0
	global_load_dwordx2 v[58:59], v3, s[0:1]
	s_add_u32 s0, s14, 0x2d000
	s_addc_u32 s1, s15, 0
	global_load_dword v106, v2, s[0:1]
	s_add_u32 s0, s4, 0xfc0
	s_addc_u32 s1, s5, 0
	global_load_dwordx2 v[60:61], v3, s[0:1]
	s_add_u32 s0, s14, 0x2f400
	s_addc_u32 s1, s15, 0
	global_load_dword v107, v2, s[0:1]
	s_add_u32 s0, s4, 0x1080
	s_addc_u32 s1, s5, 0
	global_load_dwordx2 v[62:63], v3, s[0:1]
	s_add_u32 s0, s14, 0x31800
	s_addc_u32 s1, s15, 0
	global_load_dword v108, v2, s[0:1]
	s_add_u32 s0, s4, 0x1140
	s_addc_u32 s1, s5, 0
	global_load_dwordx2 v[64:65], v3, s[0:1]
	s_add_u32 s0, s14, 0x33c00
	s_addc_u32 s1, s15, 0
	global_load_dword v109, v2, s[0:1]
	s_add_u32 s0, s4, 0x1200
	s_addc_u32 s1, s5, 0
	global_load_dwordx2 v[66:67], v3, s[0:1]
	s_add_u32 s0, s14, 0x36000
	s_addc_u32 s1, s15, 0
	global_load_dword v110, v2, s[0:1]
	s_add_u32 s0, s4, 0x12c0
	s_addc_u32 s1, s5, 0
	global_load_dwordx2 v[68:69], v3, s[0:1]
	s_add_u32 s0, s14, 0x38400
	s_addc_u32 s1, s15, 0
	global_load_dword v111, v2, s[0:1]
	s_waitcnt vmcnt(58)
; __device__ __forceinline__ unsigned pk_bf16(float lo, float hi) { unsigned r; asm volatile("v_cvt_pk_bf16_f32 %0, %1, %2" : "=v"(r) : "v"(lo), "v"(hi)); return r; }
; __device__ __forceinline__ float bflo(unsigned w) { return __uint_as_float(w << 16); }
; __device__ __forceinline__ float bfhi(unsigned w) { return __uint_as_float(w & 0xffff0000u); }
; __device__ __forceinline__ int otid(int wv) { int ln; asm volatile("v_mbcnt_lo_u32_b32 %0, -1, 0\n\tv_mbcnt_hi_u32_b32 %0, -1, %0" : "=v"(ln)); return wv * 64 + ln; }
; __device__ __forceinline__ void gla_scan(int wv, const Params& p) {
;     bf16_t* S = (bf16_t*)(p.ws + OFF_S); const float* DEC = (const float*)(p.ws + OFF_DEC);
;     for (int e = blockIdx.x * 512 + otid(wv); e < 147456; e += gridDim.x * 512) {
;         const int chain = e / 2304, idx = (e % 2304) * 2, dk = idx % 48, dir = chain & 1; const size_t base = (size_t)chain * 36;
;         float s0 = 0.f, s1 = 0.f;
;         for (int st0 = 0; st0 < 36; st0 += 6) { unsigned v[6]; float d0[6], d1[6]; unsigned* sp[6];
; #pragma unroll
;             for (int u = 0; u < 6; ++u) { const int st = st0 + u, n = dir ? 35 - st : (st < 4 ? 32 + st : st - 4); sp[u] = (unsigned*)(S + (base + n) * 4608 + idx); v[u] = *sp[u];
;                 const float* dp = DEC + (base + n) * 48 + dk; d0[u] = dp[0]; d1[u] = dp[1]; }
; #pragma unroll
;             for (int u = 0; u < 6; ++u) { *sp[u] = pk_bf16(s0, s1); s0 = s0 * d0[u] + bflo(v[u]); s1 = s1 * d1[u] + bfhi(v[u]); } }
	v_cvt_pk_bf16_f32 v4, v6, v7
	s_add_u32 s0, s14, 0x48000
	s_addc_u32 s1, s15, 0
	global_store_dword v2, v4, s[0:1]
	v_lshlrev_b32_e32 v8, 16, v82
	v_and_b32_e32 v9, 0xffff0000, v82
	v_pk_fma_f32 v[6:7], v[6:7], v[10:11], v[8:9]
	s_waitcnt vmcnt(57)
	v_cvt_pk_bf16_f32 v5, v6, v7
	s_add_u32 s0, s14, 0x4a400
	s_addc_u32 s1, s15, 0
	global_store_dword v2, v5, s[0:1]
	v_lshlrev_b32_e32 v8, 16, v83
	v_and_b32_e32 v9, 0xffff0000, v83
	v_pk_fma_f32 v[6:7], v[6:7], v[12:13], v[8:9]
	s_waitcnt vmcnt(56)
	v_cvt_pk_bf16_f32 v4, v6, v7
	s_add_u32 s0, s14, 0x4c800
	s_addc_u32 s1, s15, 0
	global_store_dword v2, v4, s[0:1]
	v_lshlrev_b32_e32 v8, 16, v84
	v_and_b32_e32 v9, 0xffff0000, v84
	v_pk_fma_f32 v[6:7], v[6:7], v[14:15], v[8:9]
	s_waitcnt vmcnt(55)
	v_cvt_pk_bf16_f32 v5, v6, v7
	s_add_u32 s0, s14, 0x4ec00
	s_addc_u32 s1, s15, 0
	global_store_dword v2, v5, s[0:1]
	v_lshlrev_b32_e32 v8, 16, v85
	v_and_b32_e32 v9, 0xffff0000, v85
	v_pk_fma_f32 v[6:7], v[6:7], v[16:17], v[8:9]
	s_waitcnt vmcnt(54)
	v_cvt_pk_bf16_f32 v4, v6, v7
	s_add_u32 s0, s14, 0x0
	s_addc_u32 s1, s15, 0
	global_store_dword v2, v4, s[0:1]
	v_lshlrev_b32_e32 v8, 16, v86
	v_and_b32_e32 v9, 0xffff0000, v86
	v_pk_fma_f32 v[6:7], v[6:7], v[18:19], v[8:9]
	s_waitcnt vmcnt(53)
	v_cvt_pk_bf16_f32 v5, v6, v7
	s_add_u32 s0, s14, 0x2400
	s_addc_u32 s1, s15, 0
	global_store_dword v2, v5, s[0:1]
	v_lshlrev_b32_e32 v8, 16, v87
	v_and_b32_e32 v9, 0xffff0000, v87
	v_pk_fma_f32 v[6:7], v[6:7], v[20:21], v[8:9]
	s_waitcnt vmcnt(52)
	v_cvt_pk_bf16_f32 v4, v6, v7
	s_add_u32 s0, s14, 0x4800
	s_addc_u32 s1, s15, 0
	global_store_dword v2, v4, s[0:1]
	v_lshlrev_b32_e32 v8, 16, v88
	v_and_b32_e32 v9, 0xffff0000, v88
	v_pk_fma_f32 v[6:7], v[6:7], v[22:23], v[8:9]
	s_waitcnt vmcnt(51)
	v_cvt_pk_bf16_f32 v5, v6, v7
	s_add_u32 s0, s14, 0x6c00
	s_addc_u32 s1, s15, 0
	global_store_dword v2, v5, s[0:1]
	v_lshlrev_b32_e32 v8, 16, v89
	v_and_b32_e32 v9, 0xffff0000, v89
	v_pk_fma_f32 v[6:7], v[6:7], v[24:25], v[8:9]
	s_waitcnt vmcnt(50)
	v_cvt_pk_bf16_f32 v4, v6, v7
	s_add_u32 s0, s14, 0x9000
	s_addc_u32 s1, s15, 0
	global_store_dword v2, v4, s[0:1]
	v_lshlrev_b32_e32 v8, 16, v90
	v_and_b32_e32 v9, 0xffff0000, v90
	v_pk_fma_f32 v[6:7], v[6:7], v[26:27], v[8:9]
	s_add_u32 s0, s4, 0x1380
	s_addc_u32 s1, s5, 0
	global_load_dwordx2 v[70:71], v3, s[0:1]
	s_add_u32 s0, s14, 0x3a800
	s_addc_u32 s1, s15, 0
	global_load_dword v112, v2, s[0:1]
	s_add_u32 s0, s4, 0x1440
	s_addc_u32 s1, s5, 0
	global_load_dwordx2 v[72:73], v3, s[0:1]
	s_add_u32 s0, s14, 0x3cc00
	s_addc_u32 s1, s15, 0
	global_load_dword v113, v2, s[0:1]
	s_add_u32 s0, s4, 0x1500
	s_addc_u32 s1, s5, 0
	global_load_dwordx2 v[74:75], v3, s[0:1]
	s_add_u32 s0, s14, 0x3f000
	s_addc_u32 s1, s15, 0
	global_load_dword v114, v2, s[0:1]
	s_add_u32 s0, s4, 0x15c0
	s_addc_u32 s1, s5, 0
	global_load_dwordx2 v[76:77], v3, s[0:1]
	s_add_u32 s0, s14, 0x41400
	s_addc_u32 s1, s15, 0
	global_load_dword v115, v2, s[0:1]
	s_add_u32 s0, s4, 0x1680
	s_addc_u32 s1, s5, 0
	global_load_dwordx2 v[78:79], v3, s[0:1]
	s_add_u32 s0, s14, 0x43800
	s_addc_u32 s1, s15, 0
	global_load_dword v116, v2, s[0:1]
	s_add_u32 s0, s4, 0x1740
	s_addc_u32 s1, s5, 0
	global_load_dwordx2 v[80:81], v3, s[0:1]
	s_add_u32 s0, s14, 0x45c00
	s_addc_u32 s1, s15, 0
	global_load_dword v117, v2, s[0:1]
	s_waitcnt vmcnt(61)
	v_cvt_pk_bf16_f32 v5, v6, v7
	s_add_u32 s0, s14, 0xb400
	s_addc_u32 s1, s15, 0
	global_store_dword v2, v5, s[0:1]
	v_lshlrev_b32_e32 v8, 16, v91
	v_and_b32_e32 v9, 0xffff0000, v91
	v_pk_fma_f32 v[6:7], v[6:7], v[28:29], v[8:9]
	s_waitcnt vmcnt(60)
	v_cvt_pk_bf16_f32 v4, v6, v7
	s_add_u32 s0, s14, 0xd800
	s_addc_u32 s1, s15, 0
	global_store_dword v2, v4, s[0:1]
	v_lshlrev_b32_e32 v8, 16, v92
	v_and_b32_e32 v9, 0xffff0000, v92
	v_pk_fma_f32 v[6:7], v[6:7], v[30:31], v[8:9]
	s_waitcnt vmcnt(59)
	v_cvt_pk_bf16_f32 v5, v6, v7
	s_add_u32 s0, s14, 0xfc00
	s_addc_u32 s1, s15, 0
	global_store_dword v2, v5, s[0:1]
	v_lshlrev_b32_e32 v8, 16, v93
	v_and_b32_e32 v9, 0xffff0000, v93
	v_pk_fma_f32 v[6:7], v[6:7], v[32:33], v[8:9]
	s_waitcnt vmcnt(58)
	v_cvt_pk_bf16_f32 v4, v6, v7
	s_add_u32 s0, s14, 0x12000
	s_addc_u32 s1, s15, 0
	global_store_dword v2, v4, s[0:1]
	v_lshlrev_b32_e32 v8, 16, v94
	v_and_b32_e32 v9, 0xffff0000, v94
	v_pk_fma_f32 v[6:7], v[6:7], v[34:35], v[8:9]
	s_waitcnt vmcnt(57)
	v_cvt_pk_bf16_f32 v5, v6, v7
	s_add_u32 s0, s14, 0x14400
	s_addc_u32 s1, s15, 0
	global_store_dword v2, v5, s[0:1]
	v_lshlrev_b32_e32 v8, 16, v95
	v_and_b32_e32 v9, 0xffff0000, v95
	v_pk_fma_f32 v[6:7], v[6:7], v[36:37], v[8:9]
	s_waitcnt vmcnt(56)
	v_cvt_pk_bf16_f32 v4, v6, v7
	s_add_u32 s0, s14, 0x16800
	s_addc_u32 s1, s15, 0
	global_store_dword v2, v4, s[0:1]
	v_lshlrev_b32_e32 v8, 16, v96
	v_and_b32_e32 v9, 0xffff0000, v96
	v_pk_fma_f32 v[6:7], v[6:7], v[38:39], v[8:9]
	s_waitcnt vmcnt(55)
	v_cvt_pk_bf16_f32 v5, v6, v7
	s_add_u32 s0, s14, 0x18c00
	s_addc_u32 s1, s15, 0
	global_store_dword v2, v5, s[0:1]
	v_lshlrev_b32_e32 v8, 16, v97
	v_and_b32_e32 v9, 0xffff0000, v97
	v_pk_fma_f32 v[6:7], v[6:7], v[40:41], v[8:9]
	s_waitcnt vmcnt(54)
	v_cvt_pk_bf16_f32 v4, v6, v7
	s_add_u32 s0, s14, 0x1b000
	s_addc_u32 s1, s15, 0
	global_store_dword v2, v4, s[0:1]
	v_lshlrev_b32_e32 v8, 16, v98
	v_and_b32_e32 v9, 0xffff0000, v98
	v_pk_fma_f32 v[6:7], v[6:7], v[42:43], v[8:9]
	s_waitcnt vmcnt(53)
	v_cvt_pk_bf16_f32 v5, v6, v7
	s_add_u32 s0, s14, 0x1d400
	s_addc_u32 s1, s15, 0
	global_store_dword v2, v5, s[0:1]
	v_lshlrev_b32_e32 v8, 16, v99
	v_and_b32_e32 v9, 0xffff0000, v99
	v_pk_fma_f32 v[6:7], v[6:7], v[44:45], v[8:9]
	s_waitcnt vmcnt(52)
; __device__ __forceinline__ unsigned pk_bf16(float lo, float hi) { unsigned r; asm volatile("v_cvt_pk_bf16_f32 %0, %1, %2" : "=v"(r) : "v"(lo), "v"(hi)); return r; }
; __device__ __forceinline__ float bflo(unsigned w) { return __uint_as_float(w << 16); }
; __device__ __forceinline__ float bfhi(unsigned w) { return __uint_as_float(w & 0xffff0000u); }
; __device__ __forceinline__ void gla_scan(int wv, const Params& p) {
;     ...
;         for (int st0 = 0; st0 < 36; st0 += 6) { unsigned v[6]; float d0[6], d1[6]; unsigned* sp[6];
; #pragma unroll
;             for (int u = 0; u < 6; ++u) { const int st = st0 + u, n = dir ? 35 - st : (st < 4 ? 32 + st : st - 4); sp[u] = (unsigned*)(S + (base + n) * 4608 + idx); v[u] = *sp[u];
;                 const float* dp = DEC + (base + n) * 48 + dk; d0[u] = dp[0]; d1[u] = dp[1]; }
; #pragma unroll
;             for (int u = 0; u < 6; ++u) { *sp[u] = pk_bf16(s0, s1); s0 = s0 * d0[u] + bflo(v[u]); s1 = s1 * d1[u] + bfhi(v[u]); } }
	v_cvt_pk_bf16_f32 v4, v6, v7
	s_add_u32 s0, s14, 0x1f800
	s_addc_u32 s1, s15, 0
	global_store_dword v2, v4, s[0:1]
	v_lshlrev_b32_e32 v8, 16, v100
	v_and_b32_e32 v9, 0xffff0000, v100
	v_pk_fma_f32 v[6:7], v[6:7], v[46:47], v[8:9]
	s_waitcnt vmcnt(51)
	v_cvt_pk_bf16_f32 v5, v6, v7
	s_add_u32 s0, s14, 0x21c00
	s_addc_u32 s1, s15, 0
	global_store_dword v2, v5, s[0:1]
	v_lshlrev_b32_e32 v8, 16, v101
	v_and_b32_e32 v9, 0xffff0000, v101
	v_pk_fma_f32 v[6:7], v[6:7], v[48:49], v[8:9]
	s_waitcnt vmcnt(50)
	v_cvt_pk_bf16_f32 v4, v6, v7
	s_add_u32 s0, s14, 0x24000
	s_addc_u32 s1, s15, 0
	global_store_dword v2, v4, s[0:1]
	v_lshlrev_b32_e32 v8, 16, v102
	v_and_b32_e32 v9, 0xffff0000, v102
	v_pk_fma_f32 v[6:7], v[6:7], v[50:51], v[8:9]
	s_waitcnt vmcnt(49)
	v_cvt_pk_bf16_f32 v5, v6, v7
	s_add_u32 s0, s14, 0x26400
	s_addc_u32 s1, s15, 0
	global_store_dword v2, v5, s[0:1]
	v_lshlrev_b32_e32 v8, 16, v103
	v_and_b32_e32 v9, 0xffff0000, v103
	v_pk_fma_f32 v[6:7], v[6:7], v[52:53], v[8:9]
	s_waitcnt vmcnt(48)
	v_cvt_pk_bf16_f32 v4, v6, v7
	s_add_u32 s0, s14, 0x28800
	s_addc_u32 s1, s15, 0
	global_store_dword v2, v4, s[0:1]
	v_lshlrev_b32_e32 v8, 16, v104
	v_and_b32_e32 v9, 0xffff0000, v104
	v_pk_fma_f32 v[6:7], v[6:7], v[54:55], v[8:9]
	s_waitcnt vmcnt(47)
	v_cvt_pk_bf16_f32 v5, v6, v7
	s_add_u32 s0, s14, 0x2ac00
	s_addc_u32 s1, s15, 0
	global_store_dword v2, v5, s[0:1]
	v_lshlrev_b32_e32 v8, 16, v105
	v_and_b32_e32 v9, 0xffff0000, v105
	v_pk_fma_f32 v[6:7], v[6:7], v[56:57], v[8:9]
	s_waitcnt vmcnt(46)
	v_cvt_pk_bf16_f32 v4, v6, v7
	s_add_u32 s0, s14, 0x2d000
	s_addc_u32 s1, s15, 0
	global_store_dword v2, v4, s[0:1]
	v_lshlrev_b32_e32 v8, 16, v106
	v_and_b32_e32 v9, 0xffff0000, v106
	v_pk_fma_f32 v[6:7], v[6:7], v[58:59], v[8:9]
	s_waitcnt vmcnt(45)
	v_cvt_pk_bf16_f32 v5, v6, v7
	s_add_u32 s0, s14, 0x2f400
	s_addc_u32 s1, s15, 0
	global_store_dword v2, v5, s[0:1]
	v_lshlrev_b32_e32 v8, 16, v107
	v_and_b32_e32 v9, 0xffff0000, v107
	v_pk_fma_f32 v[6:7], v[6:7], v[60:61], v[8:9]
	s_waitcnt vmcnt(44)
	v_cvt_pk_bf16_f32 v4, v6, v7
	s_add_u32 s0, s14, 0x31800
	s_addc_u32 s1, s15, 0
	global_store_dword v2, v4, s[0:1]
	v_lshlrev_b32_e32 v8, 16, v108
	v_and_b32_e32 v9, 0xffff0000, v108
	v_pk_fma_f32 v[6:7], v[6:7], v[62:63], v[8:9]
	s_waitcnt vmcnt(43)
	v_cvt_pk_bf16_f32 v5, v6, v7
	s_add_u32 s0, s14, 0x33c00
	s_addc_u32 s1, s15, 0
	global_store_dword v2, v5, s[0:1]
	v_lshlrev_b32_e32 v8, 16, v109
	v_and_b32_e32 v9, 0xffff0000, v109
	v_pk_fma_f32 v[6:7], v[6:7], v[64:65], v[8:9]
	s_waitcnt vmcnt(42)
	v_cvt_pk_bf16_f32 v4, v6, v7
	s_add_u32 s0, s14, 0x36000
	s_addc_u32 s1, s15, 0
	global_store_dword v2, v4, s[0:1]
	v_lshlrev_b32_e32 v8, 16, v110
	v_and_b32_e32 v9, 0xffff0000, v110
	v_pk_fma_f32 v[6:7], v[6:7], v[66:67], v[8:9]
	s_waitcnt vmcnt(41)
	v_cvt_pk_bf16_f32 v5, v6, v7
	s_add_u32 s0, s14, 0x38400
	s_addc_u32 s1, s15, 0
	global_store_dword v2, v5, s[0:1]
	v_lshlrev_b32_e32 v8, 16, v111
	v_and_b32_e32 v9, 0xffff0000, v111
	v_pk_fma_f32 v[6:7], v[6:7], v[68:69], v[8:9]
	s_waitcnt vmcnt(31)
	v_cvt_pk_bf16_f32 v4, v6, v7
	s_add_u32 s0, s14, 0x3a800
	s_addc_u32 s1, s15, 0
	global_store_dword v2, v4, s[0:1]
	v_lshlrev_b32_e32 v8, 16, v112
	v_and_b32_e32 v9, 0xffff0000, v112
	v_pk_fma_f32 v[6:7], v[6:7], v[70:71], v[8:9]
	s_waitcnt vmcnt(30)
	v_cvt_pk_bf16_f32 v5, v6, v7
	s_add_u32 s0, s14, 0x3cc00
	s_addc_u32 s1, s15, 0
	global_store_dword v2, v5, s[0:1]
	v_lshlrev_b32_e32 v8, 16, v113
	v_and_b32_e32 v9, 0xffff0000, v113
	v_pk_fma_f32 v[6:7], v[6:7], v[72:73], v[8:9]
	s_waitcnt vmcnt(29)
	v_cvt_pk_bf16_f32 v4, v6, v7
	s_add_u32 s0, s14, 0x3f000
	s_addc_u32 s1, s15, 0
	global_store_dword v2, v4, s[0:1]
	v_lshlrev_b32_e32 v8, 16, v114
	v_and_b32_e32 v9, 0xffff0000, v114
	v_pk_fma_f32 v[6:7], v[6:7], v[74:75], v[8:9]
	s_waitcnt vmcnt(28)
	v_cvt_pk_bf16_f32 v5, v6, v7
	s_add_u32 s0, s14, 0x41400
	s_addc_u32 s1, s15, 0
	global_store_dword v2, v5, s[0:1]
	v_lshlrev_b32_e32 v8, 16, v115
	v_and_b32_e32 v9, 0xffff0000, v115
	v_pk_fma_f32 v[6:7], v[6:7], v[76:77], v[8:9]
	s_waitcnt vmcnt(27)
	v_cvt_pk_bf16_f32 v4, v6, v7
	s_add_u32 s0, s14, 0x43800
	s_addc_u32 s1, s15, 0
	global_store_dword v2, v4, s[0:1]
	v_lshlrev_b32_e32 v8, 16, v116
	v_and_b32_e32 v9, 0xffff0000, v116
	v_pk_fma_f32 v[6:7], v[6:7], v[78:79], v[8:9]
	s_waitcnt vmcnt(26)
	v_cvt_pk_bf16_f32 v5, v6, v7
	s_add_u32 s0, s14, 0x45c00
	s_addc_u32 s1, s15, 0
	global_store_dword v2, v5, s[0:1]
	v_lshlrev_b32_e32 v8, 16, v117
	v_and_b32_e32 v9, 0xffff0000, v117
	v_pk_fma_f32 v[6:7], v[6:7], v[80:81], v[8:9]
	s_branch .Lscan_done
; __device__ __forceinline__ unsigned pk_bf16(float lo, float hi) { unsigned r; asm volatile("v_cvt_pk_bf16_f32 %0, %1, %2" : "=v"(r) : "v"(lo), "v"(hi)); return r; }
; __device__ __forceinline__ float bflo(unsigned w) { return __uint_as_float(w << 16); }
; __device__ __forceinline__ float bfhi(unsigned w) { return __uint_as_float(w & 0xffff0000u); }
; __device__ __forceinline__ int otid(int wv) { int ln; asm volatile("v_mbcnt_lo_u32_b32 %0, -1, 0\n\tv_mbcnt_hi_u32_b32 %0, -1, %0" : "=v"(ln)); return wv * 64 + ln; }
; __device__ __forceinline__ void gla_scan(int wv, const Params& p) {
;     ...
;     for (int e = blockIdx.x * 512 + otid(wv); e < 147456; e += gridDim.x * 512) {
;         const int chain = e / 2304, idx = (e % 2304) * 2, dk = idx % 48, dir = chain & 1; const size_t base = (size_t)chain * 36;
;         float s0 = 0.f, s1 = 0.f;
;         for (int st0 = 0; st0 < 36; st0 += 6) { unsigned v[6]; float d0[6], d1[6]; unsigned* sp[6];
; #pragma unroll
;             for (int u = 0; u < 6; ++u) { const int st = st0 + u, n = dir ? 35 - st : (st < 4 ? 32 + st : st - 4); sp[u] = (unsigned*)(S + (base + n) * 4608 + idx); v[u] = *sp[u];
;                 const float* dp = DEC + (base + n) * 48 + dk; d0[u] = dp[0]; d1[u] = dp[1]; }
; #pragma unroll
;             for (int u = 0; u < 6; ++u) { *sp[u] = pk_bf16(s0, s1); s0 = s0 * d0[u] + bflo(v[u]); s1 = s1 * d1[u] + bfhi(v[u]); } }
.Lscan_dir1:
	s_add_u32 s0, s4, 0x1a40
	s_addc_u32 s1, s5, 0
	global_load_dwordx2 v[10:11], v3, s[0:1]
	s_add_u32 s0, s14, 0x4ec00
	s_addc_u32 s1, s15, 0
	global_load_dword v82, v2, s[0:1]
	s_add_u32 s0, s4, 0x1980
	s_addc_u32 s1, s5, 0
	global_load_dwordx2 v[12:13], v3, s[0:1]
	s_add_u32 s0, s14, 0x4c800
	s_addc_u32 s1, s15, 0
	global_load_dword v83, v2, s[0:1]
	s_add_u32 s0, s4, 0x18c0
	s_addc_u32 s1, s5, 0
	global_load_dwordx2 v[14:15], v3, s[0:1]
	s_add_u32 s0, s14, 0x4a400
	s_addc_u32 s1, s15, 0
	global_load_dword v84, v2, s[0:1]
	s_add_u32 s0, s4, 0x1800
	s_addc_u32 s1, s5, 0
	global_load_dwordx2 v[16:17], v3, s[0:1]
	s_add_u32 s0, s14, 0x48000
	s_addc_u32 s1, s15, 0
	global_load_dword v85, v2, s[0:1]
	s_add_u32 s0, s4, 0x1740
	s_addc_u32 s1, s5, 0
	global_load_dwordx2 v[18:19], v3, s[0:1]
	s_add_u32 s0, s14, 0x45c00
	s_addc_u32 s1, s15, 0
	global_load_dword v86, v2, s[0:1]
	s_add_u32 s0, s4, 0x1680
	s_addc_u32 s1, s5, 0
	global_load_dwordx2 v[20:21], v3, s[0:1]
	s_add_u32 s0, s14, 0x43800
	s_addc_u32 s1, s15, 0
	global_load_dword v87, v2, s[0:1]
	s_add_u32 s0, s4, 0x15c0
	s_addc_u32 s1, s5, 0
	global_load_dwordx2 v[22:23], v3, s[0:1]
	s_add_u32 s0, s14, 0x41400
	s_addc_u32 s1, s15, 0
	global_load_dword v88, v2, s[0:1]
	s_add_u32 s0, s4, 0x1500
	s_addc_u32 s1, s5, 0
	global_load_dwordx2 v[24:25], v3, s[0:1]
	s_add_u32 s0, s14, 0x3f000
	s_addc_u32 s1, s15, 0
	global_load_dword v89, v2, s[0:1]
	s_add_u32 s0, s4, 0x1440
	s_addc_u32 s1, s5, 0
	global_load_dwordx2 v[26:27], v3, s[0:1]
	s_add_u32 s0, s14, 0x3cc00
	s_addc_u32 s1, s15, 0
	global_load_dword v90, v2, s[0:1]
	s_add_u32 s0, s4, 0x1380
	s_addc_u32 s1, s5, 0
	global_load_dwordx2 v[28:29], v3, s[0:1]
	s_add_u32 s0, s14, 0x3a800
	s_addc_u32 s1, s15, 0
	global_load_dword v91, v2, s[0:1]
	s_add_u32 s0, s4, 0x12c0
	s_addc_u32 s1, s5, 0
	global_load_dwordx2 v[30:31], v3, s[0:1]
	s_add_u32 s0, s14, 0x38400
	s_addc_u32 s1, s15, 0
	global_load_dword v92, v2, s[0:1]
	s_add_u32 s0, s4, 0x1200
	s_addc_u32 s1, s5, 0
	global_load_dwordx2 v[32:33], v3, s[0:1]
	s_add_u32 s0, s14, 0x36000
	s_addc_u32 s1, s15, 0
	global_load_dword v93, v2, s[0:1]
	s_add_u32 s0, s4, 0x1140
	s_addc_u32 s1, s5, 0
	global_load_dwordx2 v[34:35], v3, s[0:1]
	s_add_u32 s0, s14, 0x33c00
	s_addc_u32 s1, s15, 0
	global_load_dword v94, v2, s[0:1]
	s_add_u32 s0, s4, 0x1080
	s_addc_u32 s1, s5, 0
	global_load_dwordx2 v[36:37], v3, s[0:1]
	s_add_u32 s0, s14, 0x31800
	s_addc_u32 s1, s15, 0
	global_load_dword v95, v2, s[0:1]
	s_add_u32 s0, s4, 0xfc0
	s_addc_u32 s1, s5, 0
	global_load_dwordx2 v[38:39], v3, s[0:1]
	s_add_u32 s0, s14, 0x2f400
	s_addc_u32 s1, s15, 0
	global_load_dword v96, v2, s[0:1]
	s_add_u32 s0, s4, 0xf00
	s_addc_u32 s1, s5, 0
	global_load_dwordx2 v[40:41], v3, s[0:1]
	s_add_u32 s0, s14, 0x2d000
	s_addc_u32 s1, s15, 0
	global_load_dword v97, v2, s[0:1]
	s_add_u32 s0, s4, 0xe40
	s_addc_u32 s1, s5, 0
	global_load_dwordx2 v[42:43], v3, s[0:1]
	s_add_u32 s0, s14, 0x2ac00
	s_addc_u32 s1, s15, 0
	global_load_dword v98, v2, s[0:1]
	s_add_u32 s0, s4, 0xd80
	s_addc_u32 s1, s5, 0
	global_load_dwordx2 v[44:45], v3, s[0:1]
	s_add_u32 s0, s14, 0x28800
	s_addc_u32 s1, s15, 0
	global_load_dword v99, v2, s[0:1]
	s_add_u32 s0, s4, 0xcc0
	s_addc_u32 s1, s5, 0
	global_load_dwordx2 v[46:47], v3, s[0:1]
	s_add_u32 s0, s14, 0x26400
	s_addc_u32 s1, s15, 0
	global_load_dword v100, v2, s[0:1]
	s_add_u32 s0, s4, 0xc00
	s_addc_u32 s1, s5, 0
	global_load_dwordx2 v[48:49], v3, s[0:1]
	s_add_u32 s0, s14, 0x24000
	s_addc_u32 s1, s15, 0
	global_load_dword v101, v2, s[0:1]
	s_add_u32 s0, s4, 0xb40
	s_addc_u32 s1, s5, 0
	global_load_dwordx2 v[50:51], v3, s[0:1]
	s_add_u32 s0, s14, 0x21c00
	s_addc_u32 s1, s15, 0
	global_load_dword v102, v2, s[0:1]
	s_add_u32 s0, s4, 0xa80
	s_addc_u32 s1, s5, 0
	global_load_dwordx2 v[52:53], v3, s[0:1]
	s_add_u32 s0, s14, 0x1f800
	s_addc_u32 s1, s15, 0
	global_load_dword v103, v2, s[0:1]
	s_add_u32 s0, s4, 0x9c0
	s_addc_u32 s1, s5, 0
	global_load_dwordx2 v[54:55], v3, s[0:1]
	s_add_u32 s0, s14, 0x1d400
	s_addc_u32 s1, s15, 0
	global_load_dword v104, v2, s[0:1]
	s_add_u32 s0, s4, 0x900
	s_addc_u32 s1, s5, 0
	global_load_dwordx2 v[56:57], v3, s[0:1]
	s_add_u32 s0, s14, 0x1b000
	s_addc_u32 s1, s15, 0
	global_load_dword v105, v2, s[0:1]
	s_add_u32 s0, s4, 0x840
	s_addc_u32 s1, s5, 0
	global_load_dwordx2 v[58:59], v3, s[0:1]
	s_add_u32 s0, s14, 0x18c00
	s_addc_u32 s1, s15, 0
	global_load_dword v106, v2, s[0:1]
	s_add_u32 s0, s4, 0x780
	s_addc_u32 s1, s5, 0
	global_load_dwordx2 v[60:61], v3, s[0:1]
	s_add_u32 s0, s14, 0x16800
	s_addc_u32 s1, s15, 0
	global_load_dword v107, v2, s[0:1]
	s_add_u32 s0, s4, 0x6c0
	s_addc_u32 s1, s5, 0
	global_load_dwordx2 v[62:63], v3, s[0:1]
	s_add_u32 s0, s14, 0x14400
	s_addc_u32 s1, s15, 0
	global_load_dword v108, v2, s[0:1]
	s_add_u32 s0, s4, 0x600
	s_addc_u32 s1, s5, 0
	global_load_dwordx2 v[64:65], v3, s[0:1]
	s_add_u32 s0, s14, 0x12000
	s_addc_u32 s1, s15, 0
	global_load_dword v109, v2, s[0:1]
	s_add_u32 s0, s4, 0x540
	s_addc_u32 s1, s5, 0
	global_load_dwordx2 v[66:67], v3, s[0:1]
	s_add_u32 s0, s14, 0xfc00
	s_addc_u32 s1, s15, 0
	global_load_dword v110, v2, s[0:1]
	s_add_u32 s0, s4, 0x480
	s_addc_u32 s1, s5, 0
	global_load_dwordx2 v[68:69], v3, s[0:1]
	s_add_u32 s0, s14, 0xd800
	s_addc_u32 s1, s15, 0
	global_load_dword v111, v2, s[0:1]
	s_waitcnt vmcnt(58)
	v_cvt_pk_bf16_f32 v4, v6, v7
	s_add_u32 s0, s14, 0x4ec00
	s_addc_u32 s1, s15, 0
	global_store_dword v2, v4, s[0:1]
	v_lshlrev_b32_e32 v8, 16, v82
	v_and_b32_e32 v9, 0xffff0000, v82
	v_pk_fma_f32 v[6:7], v[6:7], v[10:11], v[8:9]
	s_waitcnt vmcnt(57)
; __device__ __forceinline__ unsigned pk_bf16(float lo, float hi) { unsigned r; asm volatile("v_cvt_pk_bf16_f32 %0, %1, %2" : "=v"(r) : "v"(lo), "v"(hi)); return r; }
; __device__ __forceinline__ float bflo(unsigned w) { return __uint_as_float(w << 16); }
; __device__ __forceinline__ float bfhi(unsigned w) { return __uint_as_float(w & 0xffff0000u); }
; __device__ __forceinline__ void gla_scan(int wv, const Params& p) {
;     ...
;         for (int st0 = 0; st0 < 36; st0 += 6) { unsigned v[6]; float d0[6], d1[6]; unsigned* sp[6];
; #pragma unroll
;             for (int u = 0; u < 6; ++u) { const int st = st0 + u, n = dir ? 35 - st : (st < 4 ? 32 + st : st - 4); sp[u] = (unsigned*)(S + (base + n) * 4608 + idx); v[u] = *sp[u];
;                 const float* dp = DEC + (base + n) * 48 + dk; d0[u] = dp[0]; d1[u] = dp[1]; }
; #pragma unroll
;             for (int u = 0; u < 6; ++u) { *sp[u] = pk_bf16(s0, s1); s0 = s0 * d0[u] + bflo(v[u]); s1 = s1 * d1[u] + bfhi(v[u]); } }
	v_cvt_pk_bf16_f32 v5, v6, v7
	s_add_u32 s0, s14, 0x4c800
	s_addc_u32 s1, s15, 0
	global_store_dword v2, v5, s[0:1]
	v_lshlrev_b32_e32 v8, 16, v83
	v_and_b32_e32 v9, 0xffff0000, v83
	v_pk_fma_f32 v[6:7], v[6:7], v[12:13], v[8:9]
	s_waitcnt vmcnt(56)
	v_cvt_pk_bf16_f32 v4, v6, v7
	s_add_u32 s0, s14, 0x4a400
	s_addc_u32 s1, s15, 0
	global_store_dword v2, v4, s[0:1]
	v_lshlrev_b32_e32 v8, 16, v84
	v_and_b32_e32 v9, 0xffff0000, v84
	v_pk_fma_f32 v[6:7], v[6:7], v[14:15], v[8:9]
	s_waitcnt vmcnt(55)
	v_cvt_pk_bf16_f32 v5, v6, v7
	s_add_u32 s0, s14, 0x48000
	s_addc_u32 s1, s15, 0
	global_store_dword v2, v5, s[0:1]
	v_lshlrev_b32_e32 v8, 16, v85
	v_and_b32_e32 v9, 0xffff0000, v85
	v_pk_fma_f32 v[6:7], v[6:7], v[16:17], v[8:9]
	s_waitcnt vmcnt(54)
	v_cvt_pk_bf16_f32 v4, v6, v7
	s_add_u32 s0, s14, 0x45c00
	s_addc_u32 s1, s15, 0
	global_store_dword v2, v4, s[0:1]
	v_lshlrev_b32_e32 v8, 16, v86
	v_and_b32_e32 v9, 0xffff0000, v86
	v_pk_fma_f32 v[6:7], v[6:7], v[18:19], v[8:9]
	s_waitcnt vmcnt(53)
	v_cvt_pk_bf16_f32 v5, v6, v7
	s_add_u32 s0, s14, 0x43800
	s_addc_u32 s1, s15, 0
	global_store_dword v2, v5, s[0:1]
	v_lshlrev_b32_e32 v8, 16, v87
	v_and_b32_e32 v9, 0xffff0000, v87
	v_pk_fma_f32 v[6:7], v[6:7], v[20:21], v[8:9]
	s_waitcnt vmcnt(52)
	v_cvt_pk_bf16_f32 v4, v6, v7
	s_add_u32 s0, s14, 0x41400
	s_addc_u32 s1, s15, 0
	global_store_dword v2, v4, s[0:1]
	v_lshlrev_b32_e32 v8, 16, v88
	v_and_b32_e32 v9, 0xffff0000, v88
	v_pk_fma_f32 v[6:7], v[6:7], v[22:23], v[8:9]
	s_waitcnt vmcnt(51)
	v_cvt_pk_bf16_f32 v5, v6, v7
	s_add_u32 s0, s14, 0x3f000
	s_addc_u32 s1, s15, 0
	global_store_dword v2, v5, s[0:1]
	v_lshlrev_b32_e32 v8, 16, v89
	v_and_b32_e32 v9, 0xffff0000, v89
	v_pk_fma_f32 v[6:7], v[6:7], v[24:25], v[8:9]
	s_waitcnt vmcnt(50)
	v_cvt_pk_bf16_f32 v4, v6, v7
	s_add_u32 s0, s14, 0x3cc00
	s_addc_u32 s1, s15, 0
	global_store_dword v2, v4, s[0:1]
	v_lshlrev_b32_e32 v8, 16, v90
	v_and_b32_e32 v9, 0xffff0000, v90
	v_pk_fma_f32 v[6:7], v[6:7], v[26:27], v[8:9]
	s_add_u32 s0, s4, 0x3c0
	s_addc_u32 s1, s5, 0
	global_load_dwordx2 v[70:71], v3, s[0:1]
	s_add_u32 s0, s14, 0xb400
	s_addc_u32 s1, s15, 0
	global_load_dword v112, v2, s[0:1]
	s_add_u32 s0, s4, 0x300
	s_addc_u32 s1, s5, 0
	global_load_dwordx2 v[72:73], v3, s[0:1]
	s_add_u32 s0, s14, 0x9000
	s_addc_u32 s1, s15, 0
	global_load_dword v113, v2, s[0:1]
	s_add_u32 s0, s4, 0x240
	s_addc_u32 s1, s5, 0
	global_load_dwordx2 v[74:75], v3, s[0:1]
	s_add_u32 s0, s14, 0x6c00
	s_addc_u32 s1, s15, 0
	global_load_dword v114, v2, s[0:1]
	s_add_u32 s0, s4, 0x180
	s_addc_u32 s1, s5, 0
	global_load_dwordx2 v[76:77], v3, s[0:1]
	s_add_u32 s0, s14, 0x4800
	s_addc_u32 s1, s15, 0
	global_load_dword v115, v2, s[0:1]
	s_add_u32 s0, s4, 0xc0
	s_addc_u32 s1, s5, 0
	global_load_dwordx2 v[78:79], v3, s[0:1]
	s_add_u32 s0, s14, 0x2400
	s_addc_u32 s1, s15, 0
	global_load_dword v116, v2, s[0:1]
	s_add_u32 s0, s4, 0x0
	s_addc_u32 s1, s5, 0
	global_load_dwordx2 v[80:81], v3, s[0:1]
	s_add_u32 s0, s14, 0x0
	s_addc_u32 s1, s15, 0
	global_load_dword v117, v2, s[0:1]
	s_waitcnt vmcnt(61)
	v_cvt_pk_bf16_f32 v5, v6, v7
	s_add_u32 s0, s14, 0x3a800
	s_addc_u32 s1, s15, 0
	global_store_dword v2, v5, s[0:1]
	v_lshlrev_b32_e32 v8, 16, v91
	v_and_b32_e32 v9, 0xffff0000, v91
	v_pk_fma_f32 v[6:7], v[6:7], v[28:29], v[8:9]
	s_waitcnt vmcnt(60)
	v_cvt_pk_bf16_f32 v4, v6, v7
	s_add_u32 s0, s14, 0x38400
	s_addc_u32 s1, s15, 0
	global_store_dword v2, v4, s[0:1]
	v_lshlrev_b32_e32 v8, 16, v92
	v_and_b32_e32 v9, 0xffff0000, v92
	v_pk_fma_f32 v[6:7], v[6:7], v[30:31], v[8:9]
	s_waitcnt vmcnt(59)
	v_cvt_pk_bf16_f32 v5, v6, v7
	s_add_u32 s0, s14, 0x36000
	s_addc_u32 s1, s15, 0
	global_store_dword v2, v5, s[0:1]
	v_lshlrev_b32_e32 v8, 16, v93
	v_and_b32_e32 v9, 0xffff0000, v93
	v_pk_fma_f32 v[6:7], v[6:7], v[32:33], v[8:9]
	s_waitcnt vmcnt(58)
	v_cvt_pk_bf16_f32 v4, v6, v7
	s_add_u32 s0, s14, 0x33c00
	s_addc_u32 s1, s15, 0
	global_store_dword v2, v4, s[0:1]
	v_lshlrev_b32_e32 v8, 16, v94
	v_and_b32_e32 v9, 0xffff0000, v94
	v_pk_fma_f32 v[6:7], v[6:7], v[34:35], v[8:9]
	s_waitcnt vmcnt(57)
	v_cvt_pk_bf16_f32 v5, v6, v7
	s_add_u32 s0, s14, 0x31800
	s_addc_u32 s1, s15, 0
	global_store_dword v2, v5, s[0:1]
	v_lshlrev_b32_e32 v8, 16, v95
	v_and_b32_e32 v9, 0xffff0000, v95
	v_pk_fma_f32 v[6:7], v[6:7], v[36:37], v[8:9]
	s_waitcnt vmcnt(56)
	v_cvt_pk_bf16_f32 v4, v6, v7
	s_add_u32 s0, s14, 0x2f400
	s_addc_u32 s1, s15, 0
	global_store_dword v2, v4, s[0:1]
	v_lshlrev_b32_e32 v8, 16, v96
	v_and_b32_e32 v9, 0xffff0000, v96
	v_pk_fma_f32 v[6:7], v[6:7], v[38:39], v[8:9]
	s_waitcnt vmcnt(55)
	v_cvt_pk_bf16_f32 v5, v6, v7
	s_add_u32 s0, s14, 0x2d000
	s_addc_u32 s1, s15, 0
	global_store_dword v2, v5, s[0:1]
	v_lshlrev_b32_e32 v8, 16, v97
	v_and_b32_e32 v9, 0xffff0000, v97
	v_pk_fma_f32 v[6:7], v[6:7], v[40:41], v[8:9]
	s_waitcnt vmcnt(54)
	v_cvt_pk_bf16_f32 v4, v6, v7
	s_add_u32 s0, s14, 0x2ac00
	s_addc_u32 s1, s15, 0
	global_store_dword v2, v4, s[0:1]
	v_lshlrev_b32_e32 v8, 16, v98
	v_and_b32_e32 v9, 0xffff0000, v98
	v_pk_fma_f32 v[6:7], v[6:7], v[42:43], v[8:9]
	s_waitcnt vmcnt(53)
; __device__ __forceinline__ unsigned pk_bf16(float lo, float hi) { unsigned r; asm volatile("v_cvt_pk_bf16_f32 %0, %1, %2" : "=v"(r) : "v"(lo), "v"(hi)); return r; }
; __device__ __forceinline__ float bflo(unsigned w) { return __uint_as_float(w << 16); }
; __device__ __forceinline__ float bfhi(unsigned w) { return __uint_as_float(w & 0xffff0000u); }
; __device__ __forceinline__ int otid(int wv) { int ln; asm volatile("v_mbcnt_lo_u32_b32 %0, -1, 0\n\tv_mbcnt_hi_u32_b32 %0, -1, %0" : "=v"(ln)); return wv * 64 + ln; }
; __device__ __forceinline__ void gla_scan(int wv, const Params& p) {
;     ...
;     for (int e = blockIdx.x * 512 + otid(wv); e < 147456; e += gridDim.x * 512) {
;         const int chain = e / 2304, idx = (e % 2304) * 2, dk = idx % 48, dir = chain & 1; const size_t base = (size_t)chain * 36;
;         float s0 = 0.f, s1 = 0.f;
;         for (int st0 = 0; st0 < 36; st0 += 6) { unsigned v[6]; float d0[6], d1[6]; unsigned* sp[6];
; #pragma unroll
;             for (int u = 0; u < 6; ++u) { const int st = st0 + u, n = dir ? 35 - st : (st < 4 ? 32 + st : st - 4); sp[u] = (unsigned*)(S + (base + n) * 4608 + idx); v[u] = *sp[u];
;                 const float* dp = DEC + (base + n) * 48 + dk; d0[u] = dp[0]; d1[u] = dp[1]; }
; #pragma unroll
;             for (int u = 0; u < 6; ++u) { *sp[u] = pk_bf16(s0, s1); s0 = s0 * d0[u] + bflo(v[u]); s1 = s1 * d1[u] + bfhi(v[u]); } }
;     }
	v_cvt_pk_bf16_f32 v5, v6, v7
	s_add_u32 s0, s14, 0x28800
	s_addc_u32 s1, s15, 0
	global_store_dword v2, v5, s[0:1]
	v_lshlrev_b32_e32 v8, 16, v99
	v_and_b32_e32 v9, 0xffff0000, v99
	v_pk_fma_f32 v[6:7], v[6:7], v[44:45], v[8:9]
	s_waitcnt vmcnt(52)
	v_cvt_pk_bf16_f32 v4, v6, v7
	s_add_u32 s0, s14, 0x26400
	s_addc_u32 s1, s15, 0
	global_store_dword v2, v4, s[0:1]
	v_lshlrev_b32_e32 v8, 16, v100
	v_and_b32_e32 v9, 0xffff0000, v100
	v_pk_fma_f32 v[6:7], v[6:7], v[46:47], v[8:9]
	s_waitcnt vmcnt(51)
	v_cvt_pk_bf16_f32 v5, v6, v7
	s_add_u32 s0, s14, 0x24000
	s_addc_u32 s1, s15, 0
	global_store_dword v2, v5, s[0:1]
	v_lshlrev_b32_e32 v8, 16, v101
	v_and_b32_e32 v9, 0xffff0000, v101
	v_pk_fma_f32 v[6:7], v[6:7], v[48:49], v[8:9]
	s_waitcnt vmcnt(50)
	v_cvt_pk_bf16_f32 v4, v6, v7
	s_add_u32 s0, s14, 0x21c00
	s_addc_u32 s1, s15, 0
	global_store_dword v2, v4, s[0:1]
	v_lshlrev_b32_e32 v8, 16, v102
	v_and_b32_e32 v9, 0xffff0000, v102
	v_pk_fma_f32 v[6:7], v[6:7], v[50:51], v[8:9]
	s_waitcnt vmcnt(49)
	v_cvt_pk_bf16_f32 v5, v6, v7
	s_add_u32 s0, s14, 0x1f800
	s_addc_u32 s1, s15, 0
	global_store_dword v2, v5, s[0:1]
	v_lshlrev_b32_e32 v8, 16, v103
	v_and_b32_e32 v9, 0xffff0000, v103
	v_pk_fma_f32 v[6:7], v[6:7], v[52:53], v[8:9]
	s_waitcnt vmcnt(48)
	v_cvt_pk_bf16_f32 v4, v6, v7
	s_add_u32 s0, s14, 0x1d400
	s_addc_u32 s1, s15, 0
	global_store_dword v2, v4, s[0:1]
	v_lshlrev_b32_e32 v8, 16, v104
	v_and_b32_e32 v9, 0xffff0000, v104
	v_pk_fma_f32 v[6:7], v[6:7], v[54:55], v[8:9]
	s_waitcnt vmcnt(47)
	v_cvt_pk_bf16_f32 v5, v6, v7
	s_add_u32 s0, s14, 0x1b000
	s_addc_u32 s1, s15, 0
	global_store_dword v2, v5, s[0:1]
	v_lshlrev_b32_e32 v8, 16, v105
	v_and_b32_e32 v9, 0xffff0000, v105
	v_pk_fma_f32 v[6:7], v[6:7], v[56:57], v[8:9]
	s_waitcnt vmcnt(46)
	v_cvt_pk_bf16_f32 v4, v6, v7
	s_add_u32 s0, s14, 0x18c00
	s_addc_u32 s1, s15, 0
	global_store_dword v2, v4, s[0:1]
	v_lshlrev_b32_e32 v8, 16, v106
	v_and_b32_e32 v9, 0xffff0000, v106
	v_pk_fma_f32 v[6:7], v[6:7], v[58:59], v[8:9]
	s_waitcnt vmcnt(45)
	v_cvt_pk_bf16_f32 v5, v6, v7
	s_add_u32 s0, s14, 0x16800
	s_addc_u32 s1, s15, 0
	global_store_dword v2, v5, s[0:1]
	v_lshlrev_b32_e32 v8, 16, v107
	v_and_b32_e32 v9, 0xffff0000, v107
	v_pk_fma_f32 v[6:7], v[6:7], v[60:61], v[8:9]
	s_waitcnt vmcnt(44)
	v_cvt_pk_bf16_f32 v4, v6, v7
	s_add_u32 s0, s14, 0x14400
	s_addc_u32 s1, s15, 0
	global_store_dword v2, v4, s[0:1]
	v_lshlrev_b32_e32 v8, 16, v108
	v_and_b32_e32 v9, 0xffff0000, v108
	v_pk_fma_f32 v[6:7], v[6:7], v[62:63], v[8:9]
	s_waitcnt vmcnt(43)
	v_cvt_pk_bf16_f32 v5, v6, v7
	s_add_u32 s0, s14, 0x12000
	s_addc_u32 s1, s15, 0
	global_store_dword v2, v5, s[0:1]
	v_lshlrev_b32_e32 v8, 16, v109
	v_and_b32_e32 v9, 0xffff0000, v109
	v_pk_fma_f32 v[6:7], v[6:7], v[64:65], v[8:9]
	s_waitcnt vmcnt(42)
	v_cvt_pk_bf16_f32 v4, v6, v7
	s_add_u32 s0, s14, 0xfc00
	s_addc_u32 s1, s15, 0
	global_store_dword v2, v4, s[0:1]
	v_lshlrev_b32_e32 v8, 16, v110
	v_and_b32_e32 v9, 0xffff0000, v110
	v_pk_fma_f32 v[6:7], v[6:7], v[66:67], v[8:9]
	s_waitcnt vmcnt(41)
	v_cvt_pk_bf16_f32 v5, v6, v7
	s_add_u32 s0, s14, 0xd800
	s_addc_u32 s1, s15, 0
	global_store_dword v2, v5, s[0:1]
	v_lshlrev_b32_e32 v8, 16, v111
	v_and_b32_e32 v9, 0xffff0000, v111
	v_pk_fma_f32 v[6:7], v[6:7], v[68:69], v[8:9]
	s_waitcnt vmcnt(31)
	v_cvt_pk_bf16_f32 v4, v6, v7
	s_add_u32 s0, s14, 0xb400
	s_addc_u32 s1, s15, 0
	global_store_dword v2, v4, s[0:1]
	v_lshlrev_b32_e32 v8, 16, v112
	v_and_b32_e32 v9, 0xffff0000, v112
	v_pk_fma_f32 v[6:7], v[6:7], v[70:71], v[8:9]
	s_waitcnt vmcnt(30)
	v_cvt_pk_bf16_f32 v5, v6, v7
	s_add_u32 s0, s14, 0x9000
	s_addc_u32 s1, s15, 0
	global_store_dword v2, v5, s[0:1]
	v_lshlrev_b32_e32 v8, 16, v113
	v_and_b32_e32 v9, 0xffff0000, v113
	v_pk_fma_f32 v[6:7], v[6:7], v[72:73], v[8:9]
	s_waitcnt vmcnt(29)
	v_cvt_pk_bf16_f32 v4, v6, v7
	s_add_u32 s0, s14, 0x6c00
	s_addc_u32 s1, s15, 0
	global_store_dword v2, v4, s[0:1]
	v_lshlrev_b32_e32 v8, 16, v114
	v_and_b32_e32 v9, 0xffff0000, v114
	v_pk_fma_f32 v[6:7], v[6:7], v[74:75], v[8:9]
	s_waitcnt vmcnt(28)
	v_cvt_pk_bf16_f32 v5, v6, v7
	s_add_u32 s0, s14, 0x4800
	s_addc_u32 s1, s15, 0
	global_store_dword v2, v5, s[0:1]
	v_lshlrev_b32_e32 v8, 16, v115
	v_and_b32_e32 v9, 0xffff0000, v115
	v_pk_fma_f32 v[6:7], v[6:7], v[76:77], v[8:9]
	s_waitcnt vmcnt(27)
	v_cvt_pk_bf16_f32 v4, v6, v7
	s_add_u32 s0, s14, 0x2400
	s_addc_u32 s1, s15, 0
	global_store_dword v2, v4, s[0:1]
	v_lshlrev_b32_e32 v8, 16, v116
	v_and_b32_e32 v9, 0xffff0000, v116
	v_pk_fma_f32 v[6:7], v[6:7], v[78:79], v[8:9]
	s_waitcnt vmcnt(26)
	v_cvt_pk_bf16_f32 v5, v6, v7
	s_add_u32 s0, s14, 0x0
	s_addc_u32 s1, s15, 0
	global_store_dword v2, v5, s[0:1]
	v_lshlrev_b32_e32 v8, 16, v117
	v_and_b32_e32 v9, 0xffff0000, v117
	v_pk_fma_f32 v[6:7], v[6:7], v[80:81], v[8:9]
.Lscan_done:
	v_readlane_b32 s0, v253, 31
	s_nop 1
	v_add_u32_e32 v0, s0, v0
	s_mov_b32 s0, 0x23fff
	v_cmp_lt_i32_e32 vcc, s0, v0
	s_or_b64 s[12:13], vcc, s[12:13]
	s_andn2_b64 exec, exec, s[12:13]
	s_cbranch_execnz .LBB0_884

; __device__ __forceinline__ unsigned pk_bf16(float lo, float hi) { unsigned r; asm volatile("v_cvt_pk_bf16_f32 %0, %1, %2" : "=v"(r) : "v"(lo), "v"(hi)); return r; }
; __device__ __forceinline__ float bflo(unsigned w) { return __uint_as_float(w << 16); }
; __device__ __forceinline__ float bfhi(unsigned w) { return __uint_as_float(w & 0xffff0000u); }
; __device__ __forceinline__ void phase_norm(int wv, const Params& p, int l, int which, int nrows, int nparts, const float* rgate) {
;     ...
;                     for (int jj = 0; jj < 2; ++jj) { const u32x4 w = *(const u32x4*)(XB + (size_t)row * 1024 + jj * 512 + lane * 8);
;                         v[u][2 * jj] = (f32x4){bflo(w.x), bfhi(w.x), bflo(w.y), bfhi(w.y)}; v[u][2 * jj + 1] = (f32x4){bflo(w.z), bfhi(w.z), bflo(w.w), bfhi(w.w)}; } } }
;             else {
; #pragma unroll
;                 for (int q = 0; q < 4; ++q) v[u][q] = (f32x4){0.f, 0.f, 0.f, 0.f}; } }
; #pragma unroll
;         for (int u = 0; u < 3; ++u) { const int row = row0 + u * nw;
;             if (row < nrows) { const bool lat = row < MLAT; const bool cpy = (l == 0 && which == 0 && !lat);
;                 if (!lat && nparts > 0) {
; #pragma unroll
;                     for (int jj = 0; jj < 2; ++jj) { f32x4 s0 = (f32x4){0.f, 0.f, 0.f, 0.f}, s1 = s0;
;                         for (int pt = 0; pt < nparts; ++pt) { const u32x4 w = *(const u32x4*)((const bf16_t*)(p.ws + OFF_S) + (size_t)pt * 2048 * 1024 + (size_t)(row - MLAT) * 1024 + jj * 512 + lane * 8);
;                             s0 += (f32x4){bflo(w.x), bfhi(w.x), bflo(w.y), bfhi(w.y)}; s1 += (f32x4){bflo(w.z), bfhi(w.z), bflo(w.w), bfhi(w.w)}; }
;                         v[u][2 * jj] += *(const f32x4*)(rgate + cq[2 * jj]) * s0; v[u][2 * jj + 1] += *(const f32x4*)(rgate + cq[2 * jj + 1]) * s1;
;                         u32x4 w; w.x = pk_bf16(v[u][2 * jj][0], v[u][2 * jj][1]); w.y = pk_bf16(v[u][2 * jj][2], v[u][2 * jj][3]); w.z = pk_bf16(v[u][2 * jj + 1][0], v[u][2 * jj + 1][1]); w.w = pk_bf16(v[u][2 * jj + 1][2], v[u][2 * jj + 1][3]);
;                         *(u32x4*)((bf16_t*)(p.ws + OFF_XB) + (size_t)row * 1024 + jj * 512 + lane * 8) = w; } }
.LBB0_1222:
	s_or_b64 exec, exec, s[6:7]
	v_add_u32_e32 v0, 0x4000, v58
	s_waitcnt vmcnt(1)
	v_lshlrev_b32_e32 v80, 16, v40
	v_and_b32_e32 v81, 0xffff0000, v40
	v_lshlrev_b32_e32 v40, 16, v41
	v_and_b32_e32 v41, 0xffff0000, v41
	v_lshlrev_b32_e32 v78, 16, v42
	v_and_b32_e32 v79, 0xffff0000, v42
	v_lshlrev_b32_e32 v76, 16, v43
	v_and_b32_e32 v77, 0xffff0000, v43
	s_waitcnt vmcnt(0)
	v_lshlrev_b32_e32 v74, 16, v36
	v_and_b32_e32 v75, 0xffff0000, v36
	v_lshlrev_b32_e32 v72, 16, v37
	v_and_b32_e32 v73, 0xffff0000, v37
	v_lshlrev_b32_e32 v42, 16, v38
	v_and_b32_e32 v43, 0xffff0000, v38
	v_lshlrev_b32_e32 v2, 16, v39
	v_and_b32_e32 v3, 0xffff0000, v39
	v_cmp_gt_i32_e32 vcc, s39, v0
	s_and_saveexec_b64 s[4:5], vcc
	s_xor_b64 s[6:7], exec, s[4:5]
	s_andn2_saveexec_b64 s[6:7], s[6:7]
	s_cbranch_execz .LBB0_1225
	v_mov_b32_e32 v59, v1
	v_lshlrev_b64 v[36:37], 11, v[58:59]
	v_lshl_add_u64 v[38:39], v[56:57], 0, v[36:37]
	s_waitcnt lgkmcnt(0)
	global_load_dwordx4 v[86:89], v[38:39], off
	v_add_co_u32_e32 v168, vcc, s31, v38
	s_nop 1
	v_addc_co_u32_e32 v169, vcc, 0, v39, vcc
	global_load_dwordx4 v[144:147], v[168:169], off
	v_add_co_u32_e32 v168, vcc, s68, v38
	s_nop 1
	v_addc_co_u32_e32 v169, vcc, 0, v39, vcc
	global_load_dwordx4 v[148:151], v[168:169], off
	v_add_co_u32_e32 v168, vcc, s34, v38
	s_nop 1
	v_addc_co_u32_e32 v169, vcc, 0, v39, vcc
	global_load_dwordx4 v[152:155], v[168:169], off
	global_load_dwordx4 v[156:159], v[50:51], off offset:16
	global_load_dwordx4 v[160:163], v[50:51], off
	v_lshl_add_u64 v[36:37], s[22:23], 0, v[36:37]
	s_waitcnt vmcnt(0)
	v_lshlrev_b32_e32 v96, 16, v86
	v_and_b32_e32 v97, 0xffff0000, v86
	v_lshlrev_b32_e32 v86, 16, v87
	v_and_b32_e32 v87, 0xffff0000, v87
	v_pk_add_f32 v[98:99], v[86:87], 0 op_sel_hi:[1,0]
	v_lshlrev_b32_e32 v86, 16, v88
	v_and_b32_e32 v87, 0xffff0000, v88
	v_pk_add_f32 v[102:103], v[86:87], 0 op_sel_hi:[1,0]
	v_add_co_u32_e32 v86, vcc, s31, v38
	v_lshlrev_b32_e32 v88, 16, v89
	v_and_b32_e32 v89, 0xffff0000, v89
	v_addc_co_u32_e32 v87, vcc, 0, v39, vcc
	v_pk_add_f32 v[100:101], v[88:89], 0 op_sel_hi:[1,0]
	v_mov_b32_e32 v86, v144
	v_mov_b32_e32 v87, v145
	v_mov_b32_e32 v88, v146
	v_mov_b32_e32 v89, v147
	v_pk_add_f32 v[96:97], v[96:97], 0 op_sel_hi:[1,0]
	s_waitcnt vmcnt(0)
	v_lshlrev_b32_e32 v104, 16, v86
	v_and_b32_e32 v105, 0xffff0000, v86
	v_lshlrev_b32_e32 v86, 16, v87
	v_and_b32_e32 v87, 0xffff0000, v87
	v_pk_add_f32 v[98:99], v[98:99], v[86:87]
	v_lshlrev_b32_e32 v86, 16, v88
	v_and_b32_e32 v87, 0xffff0000, v88
	v_pk_add_f32 v[102:103], v[102:103], v[86:87]
	v_add_co_u32_e32 v86, vcc, s68, v38
	v_lshlrev_b32_e32 v88, 16, v89
	v_and_b32_e32 v89, 0xffff0000, v89
	v_addc_co_u32_e32 v87, vcc, 0, v39, vcc
	v_pk_add_f32 v[100:101], v[100:101], v[88:89]
	v_mov_b32_e32 v86, v148
	v_mov_b32_e32 v87, v149
	v_mov_b32_e32 v88, v150
	v_mov_b32_e32 v89, v151
	v_pk_add_f32 v[96:97], v[96:97], v[104:105]
	v_add_co_u32_e32 v38, vcc, s34, v38
	s_waitcnt vmcnt(0)
	v_lshlrev_b32_e32 v104, 16, v86
	v_and_b32_e32 v105, 0xffff0000, v86
	v_lshlrev_b32_e32 v86, 16, v87
	v_and_b32_e32 v87, 0xffff0000, v87
	v_pk_add_f32 v[98:99], v[98:99], v[86:87]
	v_lshlrev_b32_e32 v86, 16, v88
	v_and_b32_e32 v87, 0xffff0000, v88
	v_lshlrev_b32_e32 v88, 16, v89
	v_and_b32_e32 v89, 0xffff0000, v89
	v_addc_co_u32_e32 v39, vcc, 0, v39, vcc
	v_pk_add_f32 v[100:101], v[100:101], v[88:89]
	v_pk_add_f32 v[102:103], v[102:103], v[86:87]
	v_mov_b32_e32 v86, v152
	v_mov_b32_e32 v87, v153
	v_mov_b32_e32 v88, v154
	v_mov_b32_e32 v89, v155
	v_pk_add_f32 v[96:97], v[96:97], v[104:105]
	s_waitcnt vmcnt(0)
	v_lshlrev_b32_e32 v38, 16, v86
	v_and_b32_e32 v39, 0xffff0000, v86
	v_lshlrev_b32_e32 v86, 16, v87
	v_and_b32_e32 v87, 0xffff0000, v87
	v_pk_add_f32 v[104:105], v[98:99], v[86:87]
	v_lshlrev_b32_e32 v86, 16, v88
	v_and_b32_e32 v87, 0xffff0000, v88
	v_lshlrev_b32_e32 v88, 16, v89
	v_and_b32_e32 v89, 0xffff0000, v89
	v_pk_add_f32 v[38:39], v[96:97], v[38:39]
	v_pk_add_f32 v[106:107], v[102:103], v[86:87]
	v_pk_add_f32 v[88:89], v[100:101], v[88:89]
	v_mov_b32_e32 v96, v156
	v_mov_b32_e32 v97, v157
	v_mov_b32_e32 v98, v158
	v_mov_b32_e32 v99, v159
	v_mov_b32_e32 v100, v160
	v_mov_b32_e32 v101, v161
	v_mov_b32_e32 v102, v162
	v_mov_b32_e32 v103, v163
	v_lshlrev_b64 v[86:87], 11, v[0:1]
	s_waitcnt vmcnt(1)
	v_pk_fma_f32 v[76:77], v[88:89], v[98:99], v[76:77]
	v_lshlrev_b32_e32 v88, 1, v44
	v_mov_b32_e32 v89, v1
	s_waitcnt vmcnt(0)
; __device__ __forceinline__ unsigned pk_bf16(float lo, float hi) { unsigned r; asm volatile("v_cvt_pk_bf16_f32 %0, %1, %2" : "=v"(r) : "v"(lo), "v"(hi)); return r; }
; __device__ __forceinline__ float bflo(unsigned w) { return __uint_as_float(w << 16); }
; __device__ __forceinline__ float bfhi(unsigned w) { return __uint_as_float(w & 0xffff0000u); }
; __device__ __forceinline__ void phase_norm(int wv, const Params& p, int l, int which, int nrows, int nparts, const float* rgate) {
;     ...
;                     for (int jj = 0; jj < 2; ++jj) { f32x4 s0 = (f32x4){0.f, 0.f, 0.f, 0.f}, s1 = s0;
;                         for (int pt = 0; pt < nparts; ++pt) { const u32x4 w = *(const u32x4*)((const bf16_t*)(p.ws + OFF_S) + (size_t)pt * 2048 * 1024 + (size_t)(row - MLAT) * 1024 + jj * 512 + lane * 8);
;                             s0 += (f32x4){bflo(w.x), bfhi(w.x), bflo(w.y), bfhi(w.y)}; s1 += (f32x4){bflo(w.z), bfhi(w.z), bflo(w.w), bfhi(w.w)}; }
;                         v[u][2 * jj] += *(const f32x4*)(rgate + cq[2 * jj]) * s0; v[u][2 * jj + 1] += *(const f32x4*)(rgate + cq[2 * jj + 1]) * s1;
;                         u32x4 w; w.x = pk_bf16(v[u][2 * jj][0], v[u][2 * jj][1]); w.y = pk_bf16(v[u][2 * jj][2], v[u][2 * jj][3]); w.z = pk_bf16(v[u][2 * jj + 1][0], v[u][2 * jj + 1][1]); w.w = pk_bf16(v[u][2 * jj + 1][2], v[u][2 * jj + 1][3]);
;                         *(u32x4*)((bf16_t*)(p.ws + OFF_XB) + (size_t)row * 1024 + jj * 512 + lane * 8) = w; } }
	v_pk_fma_f32 v[80:81], v[38:39], v[100:101], v[80:81]
	v_lshl_add_u64 v[38:39], v[46:47], 0, v[86:87]
	v_lshl_add_u64 v[36:37], v[36:37], 0, v[88:89]
	v_pk_fma_f32 v[40:41], v[104:105], v[102:103], v[40:41]
	v_pk_fma_f32 v[78:79], v[106:107], v[96:97], v[78:79]
	v_cvt_pk_bf16_f32 v96, v80, v81
	v_cvt_pk_bf16_f32 v97, v40, v41
	v_lshl_add_u64 v[86:87], s[22:23], 0, v[86:87]
	v_cvt_pk_bf16_f32 v98, v78, v79
	v_cvt_pk_bf16_f32 v99, v76, v77
	global_store_dwordx4 v[38:39], v[96:99], off
	v_add_co_u32_e32 v38, vcc, s35, v36
	v_lshl_add_u64 v[86:87], v[86:87], 0, v[88:89]
	s_nop 0
	v_addc_co_u32_e32 v39, vcc, 0, v37, vcc
	global_load_dwordx4 v[96:99], v[38:39], off offset:1024
	v_add_co_u32_e32 v168, vcc, s36, v36
	s_nop 1
	v_addc_co_u32_e32 v169, vcc, 0, v37, vcc
	global_load_dwordx4 v[144:147], v[168:169], off offset:1024
	v_add_co_u32_e32 v168, vcc, s37, v36
	s_nop 1
	v_addc_co_u32_e32 v169, vcc, 0, v37, vcc
	global_load_dwordx4 v[148:151], v[168:169], off offset:1024
	v_add_co_u32_e32 v168, vcc, s43, v36
	s_nop 1
	v_addc_co_u32_e32 v169, vcc, 0, v37, vcc
	global_load_dwordx4 v[152:155], v[168:169], off offset:1024
	global_load_dwordx4 v[156:159], v[52:53], off offset:16
	global_load_dwordx4 v[160:163], v[52:53], off
	s_waitcnt vmcnt(0)
	v_lshlrev_b32_e32 v38, 16, v96
	v_and_b32_e32 v39, 0xffff0000, v96
	v_lshlrev_b32_e32 v96, 16, v97
	v_and_b32_e32 v97, 0xffff0000, v97
	v_pk_add_f32 v[100:101], v[96:97], 0 op_sel_hi:[1,0]
	v_lshlrev_b32_e32 v96, 16, v98
	v_and_b32_e32 v97, 0xffff0000, v98
	v_pk_add_f32 v[104:105], v[96:97], 0 op_sel_hi:[1,0]
	v_add_co_u32_e32 v96, vcc, s36, v36
	v_lshlrev_b32_e32 v98, 16, v99
	v_and_b32_e32 v99, 0xffff0000, v99
	v_addc_co_u32_e32 v97, vcc, 0, v37, vcc
	v_pk_add_f32 v[102:103], v[98:99], 0 op_sel_hi:[1,0]
	v_mov_b32_e32 v96, v144
	v_mov_b32_e32 v97, v145
	v_mov_b32_e32 v98, v146
	v_mov_b32_e32 v99, v147
	v_pk_add_f32 v[38:39], v[38:39], 0 op_sel_hi:[1,0]
	s_waitcnt vmcnt(0)
	v_lshlrev_b32_e32 v106, 16, v96
	v_and_b32_e32 v107, 0xffff0000, v96
	v_lshlrev_b32_e32 v96, 16, v97
	v_and_b32_e32 v97, 0xffff0000, v97
	v_pk_add_f32 v[100:101], v[100:101], v[96:97]
	v_lshlrev_b32_e32 v96, 16, v98
	v_and_b32_e32 v97, 0xffff0000, v98
	v_pk_add_f32 v[104:105], v[104:105], v[96:97]
	v_add_co_u32_e32 v96, vcc, s37, v36
	v_lshlrev_b32_e32 v98, 16, v99
	v_and_b32_e32 v99, 0xffff0000, v99
	v_addc_co_u32_e32 v97, vcc, 0, v37, vcc
	v_pk_add_f32 v[102:103], v[102:103], v[98:99]
	v_mov_b32_e32 v96, v148
	v_mov_b32_e32 v97, v149
	v_mov_b32_e32 v98, v150
	v_mov_b32_e32 v99, v151
	v_pk_add_f32 v[38:39], v[38:39], v[106:107]
	v_add_co_u32_e32 v36, vcc, s43, v36
	s_waitcnt vmcnt(0)
	v_lshlrev_b32_e32 v106, 16, v96
	v_and_b32_e32 v107, 0xffff0000, v96
	v_lshlrev_b32_e32 v96, 16, v97
	v_and_b32_e32 v97, 0xffff0000, v97
	v_pk_add_f32 v[96:97], v[100:101], v[96:97]
	v_pk_add_f32 v[100:101], v[38:39], v[106:107]
	v_lshlrev_b32_e32 v38, 16, v98
	v_and_b32_e32 v39, 0xffff0000, v98
	v_lshlrev_b32_e32 v98, 16, v99
	v_and_b32_e32 v99, 0xffff0000, v99
	v_addc_co_u32_e32 v37, vcc, 0, v37, vcc
	v_pk_add_f32 v[98:99], v[102:103], v[98:99]
	v_pk_add_f32 v[102:103], v[104:105], v[38:39]
	v_mov_b32_e32 v36, v152
	v_mov_b32_e32 v37, v153
	v_mov_b32_e32 v38, v154
	v_mov_b32_e32 v39, v155
	v_add_co_u32_e32 v86, vcc, 0xc60c000, v86
	s_waitcnt vmcnt(0)
	v_lshlrev_b32_e32 v104, 16, v36
	v_and_b32_e32 v105, 0xffff0000, v36
	v_lshlrev_b32_e32 v36, 16, v37
	v_and_b32_e32 v37, 0xffff0000, v37
	v_pk_add_f32 v[100:101], v[100:101], v[104:105]
	v_pk_add_f32 v[104:105], v[96:97], v[36:37]
	v_lshlrev_b32_e32 v36, 16, v38
	v_and_b32_e32 v37, 0xffff0000, v38
	v_lshlrev_b32_e32 v38, 16, v39
	v_and_b32_e32 v39, 0xffff0000, v39
	v_pk_add_f32 v[102:103], v[102:103], v[36:37]
	v_pk_add_f32 v[106:107], v[98:99], v[38:39]
	v_mov_b32_e32 v36, v156
	v_mov_b32_e32 v37, v157
	v_mov_b32_e32 v38, v158
	v_mov_b32_e32 v39, v159
	v_mov_b32_e32 v96, v160
	v_mov_b32_e32 v97, v161
	v_mov_b32_e32 v98, v162
	v_mov_b32_e32 v99, v163
	v_addc_co_u32_e32 v87, vcc, 0, v87, vcc
	s_waitcnt vmcnt(1)
	v_pk_fma_f32 v[2:3], v[106:107], v[38:39], v[2:3]
	s_waitcnt vmcnt(0)
	v_pk_fma_f32 v[72:73], v[104:105], v[98:99], v[72:73]
	v_pk_fma_f32 v[74:75], v[100:101], v[96:97], v[74:75]
	v_pk_fma_f32 v[42:43], v[102:103], v[36:37], v[42:43]
	v_cvt_pk_bf16_f32 v36, v74, v75
	v_cvt_pk_bf16_f32 v37, v72, v73
	s_nop 0
	v_cvt_pk_bf16_f32 v38, v42, v43
	v_cvt_pk_bf16_f32 v39, v2, v3
	global_store_dwordx4 v[86:87], v[36:39], off offset:1024
	s_or_b64 exec, exec, s[6:7]
	v_mov_b32_e32 v59, 0
	s_and_saveexec_b64 s[6:7], s[16:17]
	s_cbranch_execnz .LBB0_1226

; __device__ __forceinline__ unsigned pk_bf16(float lo, float hi) { unsigned r; asm volatile("v_cvt_pk_bf16_f32 %0, %1, %2" : "=v"(r) : "v"(lo), "v"(hi)); return r; }
; __device__ __forceinline__ float bflo(unsigned w) { return __uint_as_float(w << 16); }
; __device__ __forceinline__ float bfhi(unsigned w) { return __uint_as_float(w & 0xffff0000u); }
; __device__ __forceinline__ void phase_norm(int wv, const Params& p, int l, int which, int nrows, int nparts, const float* rgate) {
;     ...
;                     for (int jj = 0; jj < 2; ++jj) { f32x4 s0 = (f32x4){0.f, 0.f, 0.f, 0.f}, s1 = s0;
;                         for (int pt = 0; pt < nparts; ++pt) { const u32x4 w = *(const u32x4*)((const bf16_t*)(p.ws + OFF_S) + (size_t)pt * 2048 * 1024 + (size_t)(row - MLAT) * 1024 + jj * 512 + lane * 8);
;                             s0 += (f32x4){bflo(w.x), bfhi(w.x), bflo(w.y), bfhi(w.y)}; s1 += (f32x4){bflo(w.z), bfhi(w.z), bflo(w.w), bfhi(w.w)}; }
;                         v[u][2 * jj] += *(const f32x4*)(rgate + cq[2 * jj]) * s0; v[u][2 * jj + 1] += *(const f32x4*)(rgate + cq[2 * jj + 1]) * s1;
;                         u32x4 w; w.x = pk_bf16(v[u][2 * jj][0], v[u][2 * jj][1]); w.y = pk_bf16(v[u][2 * jj][2], v[u][2 * jj][3]); w.z = pk_bf16(v[u][2 * jj + 1][0], v[u][2 * jj + 1][1]); w.w = pk_bf16(v[u][2 * jj + 1][2], v[u][2 * jj + 1][3]);
;                         *(u32x4*)((bf16_t*)(p.ws + OFF_XB) + (size_t)row * 1024 + jj * 512 + lane * 8) = w; } }
.LBB0_1226:
	v_cmp_lt_i32_e32 vcc, s30, v70
	s_and_saveexec_b64 s[8:9], vcc
	s_cbranch_execz .LBB0_1228
	v_mov_b32_e32 v85, v1
	v_lshlrev_b64 v[36:37], 11, v[84:85]
	v_lshl_add_u64 v[88:89], v[56:57], 0, v[36:37]
	s_waitcnt lgkmcnt(0)
	global_load_dwordx4 v[84:87], v[88:89], off
	v_add_co_u32_e32 v168, vcc, s31, v88
	s_nop 1
	v_addc_co_u32_e32 v169, vcc, 0, v89, vcc
	global_load_dwordx4 v[144:147], v[168:169], off
	v_add_co_u32_e32 v168, vcc, s68, v88
	s_nop 1
	v_addc_co_u32_e32 v169, vcc, 0, v89, vcc
	global_load_dwordx4 v[148:151], v[168:169], off
	v_add_co_u32_e32 v168, vcc, s34, v88
	s_nop 1
	v_addc_co_u32_e32 v169, vcc, 0, v89, vcc
	global_load_dwordx4 v[152:155], v[168:169], off
	global_load_dwordx4 v[156:159], v[50:51], off offset:16
	global_load_dwordx4 v[160:163], v[50:51], off
	v_mov_b32_e32 v38, v70
	v_mov_b32_e32 v39, v1
	v_lshl_add_u64 v[36:37], s[22:23], 0, v[36:37]
	s_waitcnt vmcnt(0)
	v_lshlrev_b32_e32 v96, 16, v84
	v_and_b32_e32 v97, 0xffff0000, v84
	v_lshlrev_b32_e32 v84, 16, v85
	v_and_b32_e32 v85, 0xffff0000, v85
	v_pk_add_f32 v[98:99], v[84:85], 0 op_sel_hi:[1,0]
	v_lshlrev_b32_e32 v84, 16, v86
	v_and_b32_e32 v85, 0xffff0000, v86
	v_pk_add_f32 v[102:103], v[84:85], 0 op_sel_hi:[1,0]
	v_add_co_u32_e32 v84, vcc, s31, v88
	v_lshlrev_b32_e32 v86, 16, v87
	v_and_b32_e32 v87, 0xffff0000, v87
	v_addc_co_u32_e32 v85, vcc, 0, v89, vcc
	v_pk_add_f32 v[100:101], v[86:87], 0 op_sel_hi:[1,0]
	v_mov_b32_e32 v84, v144
	v_mov_b32_e32 v85, v145
	v_mov_b32_e32 v86, v146
	v_mov_b32_e32 v87, v147
	v_pk_add_f32 v[96:97], v[96:97], 0 op_sel_hi:[1,0]
	s_waitcnt vmcnt(0)
	v_lshlrev_b32_e32 v104, 16, v84
	v_and_b32_e32 v105, 0xffff0000, v84
	v_lshlrev_b32_e32 v84, 16, v85
	v_and_b32_e32 v85, 0xffff0000, v85
	v_pk_add_f32 v[98:99], v[98:99], v[84:85]
	v_lshlrev_b32_e32 v84, 16, v86
	v_and_b32_e32 v85, 0xffff0000, v86
	v_pk_add_f32 v[102:103], v[102:103], v[84:85]
	v_add_co_u32_e32 v84, vcc, s68, v88
	v_lshlrev_b32_e32 v86, 16, v87
	v_and_b32_e32 v87, 0xffff0000, v87
	v_addc_co_u32_e32 v85, vcc, 0, v89, vcc
	v_pk_add_f32 v[100:101], v[100:101], v[86:87]
	v_mov_b32_e32 v84, v148
	v_mov_b32_e32 v85, v149
	v_mov_b32_e32 v86, v150
	v_mov_b32_e32 v87, v151
	v_pk_add_f32 v[96:97], v[96:97], v[104:105]
	s_waitcnt vmcnt(0)
	v_lshlrev_b32_e32 v104, 16, v84
	v_and_b32_e32 v105, 0xffff0000, v84
	v_lshlrev_b32_e32 v84, 16, v85
	v_and_b32_e32 v85, 0xffff0000, v85
	v_pk_add_f32 v[98:99], v[98:99], v[84:85]
	v_lshlrev_b32_e32 v84, 16, v86
	v_and_b32_e32 v85, 0xffff0000, v86
	v_pk_add_f32 v[102:103], v[102:103], v[84:85]
	v_add_co_u32_e32 v84, vcc, s34, v88
	v_lshlrev_b32_e32 v86, 16, v87
	v_and_b32_e32 v87, 0xffff0000, v87
	v_addc_co_u32_e32 v85, vcc, 0, v89, vcc
	v_pk_add_f32 v[100:101], v[100:101], v[86:87]
	v_mov_b32_e32 v84, v152
	v_mov_b32_e32 v85, v153
	v_mov_b32_e32 v86, v154
	v_mov_b32_e32 v87, v155
	v_pk_add_f32 v[96:97], v[96:97], v[104:105]
	s_waitcnt vmcnt(0)
	v_lshlrev_b32_e32 v88, 16, v84
	v_and_b32_e32 v89, 0xffff0000, v84
	v_lshlrev_b32_e32 v84, 16, v85
	v_and_b32_e32 v85, 0xffff0000, v85
	v_pk_add_f32 v[106:107], v[98:99], v[84:85]
	v_lshlrev_b32_e32 v84, 16, v86
	v_and_b32_e32 v85, 0xffff0000, v86
	v_lshlrev_b32_e32 v86, 16, v87
	v_and_b32_e32 v87, 0xffff0000, v87
	v_pk_add_f32 v[104:105], v[96:97], v[88:89]
	v_pk_add_f32 v[100:101], v[100:101], v[86:87]
	v_mov_b32_e32 v86, v156
	v_mov_b32_e32 v87, v157
	v_mov_b32_e32 v88, v158
	v_mov_b32_e32 v89, v159
	v_mov_b32_e32 v96, v160
	v_mov_b32_e32 v97, v161
	v_mov_b32_e32 v98, v162
	v_mov_b32_e32 v99, v163
	v_pk_add_f32 v[102:103], v[102:103], v[84:85]
	v_lshlrev_b64 v[84:85], 11, v[38:39]
	v_lshl_add_u64 v[38:39], v[46:47], 0, v[84:85]
	v_lshl_add_u64 v[84:85], s[22:23], 0, v[84:85]
	s_waitcnt vmcnt(1)
	v_pk_fma_f32 v[28:29], v[102:103], v[86:87], v[28:29]
	s_waitcnt vmcnt(0)
; __device__ __forceinline__ unsigned pk_bf16(float lo, float hi) { unsigned r; asm volatile("v_cvt_pk_bf16_f32 %0, %1, %2" : "=v"(r) : "v"(lo), "v"(hi)); return r; }
; __device__ __forceinline__ float bflo(unsigned w) { return __uint_as_float(w << 16); }
; __device__ __forceinline__ float bfhi(unsigned w) { return __uint_as_float(w & 0xffff0000u); }
; __device__ __forceinline__ void phase_norm(int wv, const Params& p, int l, int which, int nrows, int nparts, const float* rgate) {
;     ...
;                     for (int jj = 0; jj < 2; ++jj) { f32x4 s0 = (f32x4){0.f, 0.f, 0.f, 0.f}, s1 = s0;
;                         for (int pt = 0; pt < nparts; ++pt) { const u32x4 w = *(const u32x4*)((const bf16_t*)(p.ws + OFF_S) + (size_t)pt * 2048 * 1024 + (size_t)(row - MLAT) * 1024 + jj * 512 + lane * 8);
;                             s0 += (f32x4){bflo(w.x), bfhi(w.x), bflo(w.y), bfhi(w.y)}; s1 += (f32x4){bflo(w.z), bfhi(w.z), bflo(w.w), bfhi(w.w)}; }
;                         v[u][2 * jj] += *(const f32x4*)(rgate + cq[2 * jj]) * s0; v[u][2 * jj + 1] += *(const f32x4*)(rgate + cq[2 * jj + 1]) * s1;
;                         u32x4 w; w.x = pk_bf16(v[u][2 * jj][0], v[u][2 * jj][1]); w.y = pk_bf16(v[u][2 * jj][2], v[u][2 * jj][3]); w.z = pk_bf16(v[u][2 * jj + 1][0], v[u][2 * jj + 1][1]); w.w = pk_bf16(v[u][2 * jj + 1][2], v[u][2 * jj + 1][3]);
;                         *(u32x4*)((bf16_t*)(p.ws + OFF_XB) + (size_t)row * 1024 + jj * 512 + lane * 8) = w; } }
	v_pk_fma_f32 v[34:35], v[106:107], v[98:99], v[34:35]
	v_pk_fma_f32 v[32:33], v[104:105], v[96:97], v[32:33]
	v_pk_fma_f32 v[30:31], v[100:101], v[88:89], v[30:31]
	v_cvt_pk_bf16_f32 v86, v32, v33
	v_cvt_pk_bf16_f32 v87, v34, v35
	v_cvt_pk_bf16_f32 v88, v28, v29
	s_nop 0
	v_cvt_pk_bf16_f32 v89, v30, v31
	global_store_dwordx4 v[38:39], v[86:89], off
	s_nop 1
	v_lshlrev_b32_e32 v86, 1, v44
	v_mov_b32_e32 v87, v1
	v_lshl_add_u64 v[36:37], v[36:37], 0, v[86:87]
	v_add_co_u32_e32 v38, vcc, s35, v36
	v_lshl_add_u64 v[84:85], v[84:85], 0, v[86:87]
	s_nop 0
	v_addc_co_u32_e32 v39, vcc, 0, v37, vcc
	global_load_dwordx4 v[96:99], v[38:39], off offset:1024
	v_add_co_u32_e32 v168, vcc, s36, v36
	s_nop 1
	v_addc_co_u32_e32 v169, vcc, 0, v37, vcc
	global_load_dwordx4 v[144:147], v[168:169], off offset:1024
	v_add_co_u32_e32 v168, vcc, s37, v36
	s_nop 1
	v_addc_co_u32_e32 v169, vcc, 0, v37, vcc
	global_load_dwordx4 v[148:151], v[168:169], off offset:1024
	v_add_co_u32_e32 v168, vcc, s43, v36
	s_nop 1
	v_addc_co_u32_e32 v169, vcc, 0, v37, vcc
	global_load_dwordx4 v[152:155], v[168:169], off offset:1024
	global_load_dwordx4 v[156:159], v[52:53], off offset:16
	global_load_dwordx4 v[160:163], v[52:53], off
	s_waitcnt vmcnt(0)
	v_lshlrev_b32_e32 v38, 16, v96
	v_and_b32_e32 v39, 0xffff0000, v96
	v_lshlrev_b32_e32 v88, 16, v97
	v_and_b32_e32 v89, 0xffff0000, v97
	v_lshlrev_b32_e32 v96, 16, v98
	v_and_b32_e32 v97, 0xffff0000, v98
	v_pk_add_f32 v[102:103], v[96:97], 0 op_sel_hi:[1,0]
	v_add_co_u32_e32 v96, vcc, s36, v36
	v_lshlrev_b32_e32 v98, 16, v99
	v_and_b32_e32 v99, 0xffff0000, v99
	v_addc_co_u32_e32 v97, vcc, 0, v37, vcc
	v_pk_add_f32 v[100:101], v[98:99], 0 op_sel_hi:[1,0]
	v_mov_b32_e32 v96, v144
	v_mov_b32_e32 v97, v145
	v_mov_b32_e32 v98, v146
	v_mov_b32_e32 v99, v147
	v_pk_add_f32 v[88:89], v[88:89], 0 op_sel_hi:[1,0]
	v_pk_add_f32 v[38:39], v[38:39], 0 op_sel_hi:[1,0]
	s_waitcnt vmcnt(0)
	v_lshlrev_b32_e32 v104, 16, v96
	v_and_b32_e32 v105, 0xffff0000, v96
	v_lshlrev_b32_e32 v96, 16, v97
	v_and_b32_e32 v97, 0xffff0000, v97
	v_pk_add_f32 v[88:89], v[88:89], v[96:97]
	v_lshlrev_b32_e32 v96, 16, v98
	v_and_b32_e32 v97, 0xffff0000, v98
	v_pk_add_f32 v[102:103], v[102:103], v[96:97]
	v_add_co_u32_e32 v96, vcc, s37, v36
	v_lshlrev_b32_e32 v98, 16, v99
	v_and_b32_e32 v99, 0xffff0000, v99
	v_addc_co_u32_e32 v97, vcc, 0, v37, vcc
	v_pk_add_f32 v[100:101], v[100:101], v[98:99]
	v_mov_b32_e32 v96, v148
	v_mov_b32_e32 v97, v149
	v_mov_b32_e32 v98, v150
	v_mov_b32_e32 v99, v151
	v_pk_add_f32 v[38:39], v[38:39], v[104:105]
	v_add_co_u32_e32 v36, vcc, s43, v36
	s_waitcnt vmcnt(0)
	v_lshlrev_b32_e32 v104, 16, v96
	v_and_b32_e32 v105, 0xffff0000, v96
	v_lshlrev_b32_e32 v96, 16, v97
	v_and_b32_e32 v97, 0xffff0000, v97
	v_pk_add_f32 v[88:89], v[88:89], v[96:97]
	v_pk_add_f32 v[96:97], v[38:39], v[104:105]
	v_lshlrev_b32_e32 v38, 16, v98
	v_and_b32_e32 v39, 0xffff0000, v98
	v_lshlrev_b32_e32 v98, 16, v99
	v_and_b32_e32 v99, 0xffff0000, v99
	v_addc_co_u32_e32 v37, vcc, 0, v37, vcc
	v_pk_add_f32 v[98:99], v[100:101], v[98:99]
	v_pk_add_f32 v[100:101], v[102:103], v[38:39]
	v_mov_b32_e32 v36, v152
	v_mov_b32_e32 v37, v153
	v_mov_b32_e32 v38, v154
	v_mov_b32_e32 v39, v155
	v_add_co_u32_e32 v84, vcc, 0xc60c000, v84
	s_waitcnt vmcnt(0)
	v_lshlrev_b32_e32 v102, 16, v36
	v_and_b32_e32 v103, 0xffff0000, v36
	v_lshlrev_b32_e32 v36, 16, v37
	v_and_b32_e32 v37, 0xffff0000, v37
	v_pk_add_f32 v[88:89], v[88:89], v[36:37]
	v_lshlrev_b32_e32 v36, 16, v38
	v_and_b32_e32 v37, 0xffff0000, v38
	v_lshlrev_b32_e32 v38, 16, v39
	v_and_b32_e32 v39, 0xffff0000, v39
	v_pk_add_f32 v[102:103], v[96:97], v[102:103]
	v_pk_add_f32 v[100:101], v[100:101], v[36:37]
	v_pk_add_f32 v[104:105], v[98:99], v[38:39]
	v_mov_b32_e32 v36, v156
	v_mov_b32_e32 v37, v157
	v_mov_b32_e32 v38, v158
	v_mov_b32_e32 v39, v159
	v_mov_b32_e32 v96, v160
	v_mov_b32_e32 v97, v161
	v_mov_b32_e32 v98, v162
	v_mov_b32_e32 v99, v163
	v_addc_co_u32_e32 v85, vcc, 0, v85, vcc
	s_waitcnt vmcnt(1)
	v_pk_fma_f32 v[22:23], v[104:105], v[38:39], v[22:23]
	s_waitcnt vmcnt(0)
	v_pk_fma_f32 v[26:27], v[88:89], v[98:99], v[26:27]
	v_pk_fma_f32 v[24:25], v[102:103], v[96:97], v[24:25]
	v_pk_fma_f32 v[20:21], v[100:101], v[36:37], v[20:21]
	v_cvt_pk_bf16_f32 v36, v24, v25
	v_cvt_pk_bf16_f32 v37, v26, v27
	s_nop 0
	v_cvt_pk_bf16_f32 v38, v20, v21
	v_cvt_pk_bf16_f32 v39, v22, v23
	global_store_dwordx4 v[84:85], v[36:39], off offset:1024

; __device__ __forceinline__ unsigned pk_bf16(float lo, float hi) { unsigned r; asm volatile("v_cvt_pk_bf16_f32 %0, %1, %2" : "=v"(r) : "v"(lo), "v"(hi)); return r; }
; __device__ __forceinline__ float bflo(unsigned w) { return __uint_as_float(w << 16); }
; __device__ __forceinline__ float bfhi(unsigned w) { return __uint_as_float(w & 0xffff0000u); }
; __device__ __forceinline__ void phase_norm(int wv, const Params& p, int l, int which, int nrows, int nparts, const float* rgate) {
;     ...
;                     for (int jj = 0; jj < 2; ++jj) { f32x4 s0 = (f32x4){0.f, 0.f, 0.f, 0.f}, s1 = s0;
;                         for (int pt = 0; pt < nparts; ++pt) { const u32x4 w = *(const u32x4*)((const bf16_t*)(p.ws + OFF_S) + (size_t)pt * 2048 * 1024 + (size_t)(row - MLAT) * 1024 + jj * 512 + lane * 8);
;                             s0 += (f32x4){bflo(w.x), bfhi(w.x), bflo(w.y), bfhi(w.y)}; s1 += (f32x4){bflo(w.z), bfhi(w.z), bflo(w.w), bfhi(w.w)}; }
;                         v[u][2 * jj] += *(const f32x4*)(rgate + cq[2 * jj]) * s0; v[u][2 * jj + 1] += *(const f32x4*)(rgate + cq[2 * jj + 1]) * s1;
;                         u32x4 w; w.x = pk_bf16(v[u][2 * jj][0], v[u][2 * jj][1]); w.y = pk_bf16(v[u][2 * jj][2], v[u][2 * jj][3]); w.z = pk_bf16(v[u][2 * jj + 1][0], v[u][2 * jj + 1][1]); w.w = pk_bf16(v[u][2 * jj + 1][2], v[u][2 * jj + 1][3]);
;                         *(u32x4*)((bf16_t*)(p.ws + OFF_XB) + (size_t)row * 1024 + jj * 512 + lane * 8) = w; } }
.LBB0_1229:
	v_cmp_lt_i32_e32 vcc, s30, v68
	s_and_saveexec_b64 s[8:9], vcc
	s_cbranch_execz .LBB0_1231
	v_mov_b32_e32 v83, v1
	v_lshlrev_b64 v[36:37], 11, v[82:83]
	s_waitcnt lgkmcnt(0)
	v_lshl_add_u64 v[86:87], v[56:57], 0, v[36:37]
	global_load_dwordx4 v[82:85], v[86:87], off
	v_add_co_u32_e32 v168, vcc, s31, v86
	s_nop 1
	v_addc_co_u32_e32 v169, vcc, 0, v87, vcc
	global_load_dwordx4 v[144:147], v[168:169], off
	v_add_co_u32_e32 v168, vcc, s68, v86
	s_nop 1
	v_addc_co_u32_e32 v169, vcc, 0, v87, vcc
	global_load_dwordx4 v[148:151], v[168:169], off
	v_add_co_u32_e32 v168, vcc, s34, v86
	s_nop 1
	v_addc_co_u32_e32 v169, vcc, 0, v87, vcc
	global_load_dwordx4 v[152:155], v[168:169], off
	global_load_dwordx4 v[156:159], v[50:51], off offset:16
	global_load_dwordx4 v[160:163], v[50:51], off
	v_mov_b32_e32 v38, v68
	v_mov_b32_e32 v39, v1
	v_lshl_add_u64 v[36:37], s[22:23], 0, v[36:37]
	s_waitcnt vmcnt(0)
	v_lshlrev_b32_e32 v88, 16, v82
	v_and_b32_e32 v89, 0xffff0000, v82
	v_lshlrev_b32_e32 v82, 16, v83
	v_and_b32_e32 v83, 0xffff0000, v83
	v_pk_add_f32 v[96:97], v[82:83], 0 op_sel_hi:[1,0]
	v_lshlrev_b32_e32 v82, 16, v84
	v_and_b32_e32 v83, 0xffff0000, v84
	v_pk_add_f32 v[100:101], v[82:83], 0 op_sel_hi:[1,0]
	v_add_co_u32_e32 v82, vcc, s31, v86
	v_lshlrev_b32_e32 v84, 16, v85
	v_and_b32_e32 v85, 0xffff0000, v85
	v_addc_co_u32_e32 v83, vcc, 0, v87, vcc
	v_pk_add_f32 v[98:99], v[84:85], 0 op_sel_hi:[1,0]
	v_mov_b32_e32 v82, v144
	v_mov_b32_e32 v83, v145
	v_mov_b32_e32 v84, v146
	v_mov_b32_e32 v85, v147
	v_pk_add_f32 v[88:89], v[88:89], 0 op_sel_hi:[1,0]
	s_waitcnt vmcnt(0)
	v_lshlrev_b32_e32 v102, 16, v82
	v_and_b32_e32 v103, 0xffff0000, v82
	v_lshlrev_b32_e32 v82, 16, v83
	v_and_b32_e32 v83, 0xffff0000, v83
	v_pk_add_f32 v[96:97], v[96:97], v[82:83]
	v_lshlrev_b32_e32 v82, 16, v84
	v_and_b32_e32 v83, 0xffff0000, v84
	v_pk_add_f32 v[100:101], v[100:101], v[82:83]
	v_add_co_u32_e32 v82, vcc, s68, v86
	v_lshlrev_b32_e32 v84, 16, v85
	v_and_b32_e32 v85, 0xffff0000, v85
	v_addc_co_u32_e32 v83, vcc, 0, v87, vcc
	v_pk_add_f32 v[98:99], v[98:99], v[84:85]
	v_mov_b32_e32 v82, v148
	v_mov_b32_e32 v83, v149
	v_mov_b32_e32 v84, v150
	v_mov_b32_e32 v85, v151
	v_pk_add_f32 v[88:89], v[88:89], v[102:103]
	s_waitcnt vmcnt(0)
	v_lshlrev_b32_e32 v102, 16, v82
	v_and_b32_e32 v103, 0xffff0000, v82
	v_lshlrev_b32_e32 v82, 16, v83
	v_and_b32_e32 v83, 0xffff0000, v83
	v_pk_add_f32 v[96:97], v[96:97], v[82:83]
	v_lshlrev_b32_e32 v82, 16, v84
	v_and_b32_e32 v83, 0xffff0000, v84
	v_pk_add_f32 v[100:101], v[100:101], v[82:83]
	v_add_co_u32_e32 v82, vcc, s34, v86
	v_lshlrev_b32_e32 v84, 16, v85
	v_and_b32_e32 v85, 0xffff0000, v85
	v_addc_co_u32_e32 v83, vcc, 0, v87, vcc
	v_pk_add_f32 v[98:99], v[98:99], v[84:85]
	v_mov_b32_e32 v82, v152
	v_mov_b32_e32 v83, v153
	v_mov_b32_e32 v84, v154
	v_mov_b32_e32 v85, v155
	v_pk_add_f32 v[88:89], v[88:89], v[102:103]
	s_waitcnt vmcnt(0)
	v_lshlrev_b32_e32 v86, 16, v82
	v_and_b32_e32 v87, 0xffff0000, v82
	v_lshlrev_b32_e32 v82, 16, v83
	v_and_b32_e32 v83, 0xffff0000, v83
	v_pk_add_f32 v[102:103], v[96:97], v[82:83]
	v_lshlrev_b32_e32 v82, 16, v84
	v_and_b32_e32 v83, 0xffff0000, v84
	v_lshlrev_b32_e32 v84, 16, v85
	v_and_b32_e32 v85, 0xffff0000, v85
	v_pk_add_f32 v[88:89], v[88:89], v[86:87]
	v_pk_add_f32 v[104:105], v[98:99], v[84:85]
	v_mov_b32_e32 v84, v156
	v_mov_b32_e32 v85, v157
	v_mov_b32_e32 v86, v158
	v_mov_b32_e32 v87, v159
	v_mov_b32_e32 v96, v160
	v_mov_b32_e32 v97, v161
	v_mov_b32_e32 v98, v162
	v_mov_b32_e32 v99, v163
	v_pk_add_f32 v[100:101], v[100:101], v[82:83]
	v_lshlrev_b64 v[82:83], 11, v[38:39]
	v_lshl_add_u64 v[38:39], v[46:47], 0, v[82:83]
	v_lshl_add_u64 v[82:83], s[22:23], 0, v[82:83]
	s_waitcnt vmcnt(1)
	v_pk_fma_f32 v[12:13], v[100:101], v[84:85], v[12:13]
	s_waitcnt vmcnt(0)
; __device__ __forceinline__ unsigned pk_bf16(float lo, float hi) { unsigned r; asm volatile("v_cvt_pk_bf16_f32 %0, %1, %2" : "=v"(r) : "v"(lo), "v"(hi)); return r; }
; __device__ __forceinline__ float bflo(unsigned w) { return __uint_as_float(w << 16); }
; __device__ __forceinline__ float bfhi(unsigned w) { return __uint_as_float(w & 0xffff0000u); }
; __device__ __forceinline__ void phase_norm(int wv, const Params& p, int l, int which, int nrows, int nparts, const float* rgate) {
;     ...
;                     for (int jj = 0; jj < 2; ++jj) { f32x4 s0 = (f32x4){0.f, 0.f, 0.f, 0.f}, s1 = s0;
;                         for (int pt = 0; pt < nparts; ++pt) { const u32x4 w = *(const u32x4*)((const bf16_t*)(p.ws + OFF_S) + (size_t)pt * 2048 * 1024 + (size_t)(row - MLAT) * 1024 + jj * 512 + lane * 8);
;                             s0 += (f32x4){bflo(w.x), bfhi(w.x), bflo(w.y), bfhi(w.y)}; s1 += (f32x4){bflo(w.z), bfhi(w.z), bflo(w.w), bfhi(w.w)}; }
;                         v[u][2 * jj] += *(const f32x4*)(rgate + cq[2 * jj]) * s0; v[u][2 * jj + 1] += *(const f32x4*)(rgate + cq[2 * jj + 1]) * s1;
;                         u32x4 w; w.x = pk_bf16(v[u][2 * jj][0], v[u][2 * jj][1]); w.y = pk_bf16(v[u][2 * jj][2], v[u][2 * jj][3]); w.z = pk_bf16(v[u][2 * jj + 1][0], v[u][2 * jj + 1][1]); w.w = pk_bf16(v[u][2 * jj + 1][2], v[u][2 * jj + 1][3]);
;                         *(u32x4*)((bf16_t*)(p.ws + OFF_XB) + (size_t)row * 1024 + jj * 512 + lane * 8) = w; } }
	v_pk_fma_f32 v[18:19], v[102:103], v[98:99], v[18:19]
	v_pk_fma_f32 v[16:17], v[88:89], v[96:97], v[16:17]
	v_pk_fma_f32 v[14:15], v[104:105], v[86:87], v[14:15]
	v_cvt_pk_bf16_f32 v84, v16, v17
	v_cvt_pk_bf16_f32 v85, v18, v19
	v_cvt_pk_bf16_f32 v86, v12, v13
	s_nop 0
	v_cvt_pk_bf16_f32 v87, v14, v15
	global_store_dwordx4 v[38:39], v[84:87], off
	s_nop 1
	v_lshlrev_b32_e32 v84, 1, v44
	v_mov_b32_e32 v85, v1
	v_lshl_add_u64 v[36:37], v[36:37], 0, v[84:85]
	v_add_co_u32_e32 v38, vcc, s35, v36
	v_lshl_add_u64 v[82:83], v[82:83], 0, v[84:85]
	s_nop 0
	v_addc_co_u32_e32 v39, vcc, 0, v37, vcc
	global_load_dwordx4 v[86:89], v[38:39], off offset:1024
	v_add_co_u32_e32 v168, vcc, s36, v36
	s_nop 1
	v_addc_co_u32_e32 v169, vcc, 0, v37, vcc
	global_load_dwordx4 v[144:147], v[168:169], off offset:1024
	v_add_co_u32_e32 v168, vcc, s37, v36
	s_nop 1
	v_addc_co_u32_e32 v169, vcc, 0, v37, vcc
	global_load_dwordx4 v[148:151], v[168:169], off offset:1024
	v_add_co_u32_e32 v168, vcc, s43, v36
	s_nop 1
	v_addc_co_u32_e32 v169, vcc, 0, v37, vcc
	global_load_dwordx4 v[152:155], v[168:169], off offset:1024
	global_load_dwordx4 v[156:159], v[52:53], off offset:16
	global_load_dwordx4 v[160:163], v[52:53], off
	s_waitcnt vmcnt(0)
	v_lshlrev_b32_e32 v38, 16, v86
	v_and_b32_e32 v39, 0xffff0000, v86
	v_lshlrev_b32_e32 v86, 16, v87
	v_and_b32_e32 v87, 0xffff0000, v87
	v_pk_add_f32 v[96:97], v[86:87], 0 op_sel_hi:[1,0]
	v_lshlrev_b32_e32 v86, 16, v88
	v_and_b32_e32 v87, 0xffff0000, v88
	v_pk_add_f32 v[100:101], v[86:87], 0 op_sel_hi:[1,0]
	v_add_co_u32_e32 v86, vcc, s36, v36
	v_lshlrev_b32_e32 v88, 16, v89
	v_and_b32_e32 v89, 0xffff0000, v89
	v_addc_co_u32_e32 v87, vcc, 0, v37, vcc
	v_pk_add_f32 v[98:99], v[88:89], 0 op_sel_hi:[1,0]
	v_mov_b32_e32 v86, v144
	v_mov_b32_e32 v87, v145
	v_mov_b32_e32 v88, v146
	v_mov_b32_e32 v89, v147
	v_pk_add_f32 v[38:39], v[38:39], 0 op_sel_hi:[1,0]
	s_waitcnt vmcnt(0)
	v_lshlrev_b32_e32 v102, 16, v86
	v_and_b32_e32 v103, 0xffff0000, v86
	v_lshlrev_b32_e32 v86, 16, v87
	v_and_b32_e32 v87, 0xffff0000, v87
	v_pk_add_f32 v[96:97], v[96:97], v[86:87]
	v_lshlrev_b32_e32 v86, 16, v88
	v_and_b32_e32 v87, 0xffff0000, v88
	v_pk_add_f32 v[100:101], v[100:101], v[86:87]
	v_add_co_u32_e32 v86, vcc, s37, v36
	v_lshlrev_b32_e32 v88, 16, v89
	v_and_b32_e32 v89, 0xffff0000, v89
	v_addc_co_u32_e32 v87, vcc, 0, v37, vcc
	v_pk_add_f32 v[98:99], v[98:99], v[88:89]
	v_mov_b32_e32 v86, v148
	v_mov_b32_e32 v87, v149
	v_mov_b32_e32 v88, v150
	v_mov_b32_e32 v89, v151
	v_pk_add_f32 v[38:39], v[38:39], v[102:103]
	v_add_co_u32_e32 v36, vcc, s43, v36
	s_waitcnt vmcnt(0)
	v_lshlrev_b32_e32 v102, 16, v86
	v_and_b32_e32 v103, 0xffff0000, v86
	v_lshlrev_b32_e32 v86, 16, v87
	v_and_b32_e32 v87, 0xffff0000, v87
	v_pk_add_f32 v[86:87], v[96:97], v[86:87]
	v_pk_add_f32 v[96:97], v[38:39], v[102:103]
	v_lshlrev_b32_e32 v38, 16, v88
	v_and_b32_e32 v39, 0xffff0000, v88
	v_lshlrev_b32_e32 v88, 16, v89
	v_and_b32_e32 v89, 0xffff0000, v89
	v_addc_co_u32_e32 v37, vcc, 0, v37, vcc
	v_pk_add_f32 v[88:89], v[98:99], v[88:89]
	v_pk_add_f32 v[98:99], v[100:101], v[38:39]
	v_mov_b32_e32 v36, v152
	v_mov_b32_e32 v37, v153
	v_mov_b32_e32 v38, v154
	v_mov_b32_e32 v39, v155
	v_add_co_u32_e32 v82, vcc, 0xc60c000, v82
	s_waitcnt vmcnt(0)
	v_lshlrev_b32_e32 v100, 16, v36
	v_and_b32_e32 v101, 0xffff0000, v36
	v_lshlrev_b32_e32 v36, 16, v37
	v_and_b32_e32 v37, 0xffff0000, v37
	v_pk_add_f32 v[96:97], v[96:97], v[100:101]
	v_pk_add_f32 v[100:101], v[86:87], v[36:37]
	v_lshlrev_b32_e32 v36, 16, v38
	v_and_b32_e32 v37, 0xffff0000, v38
	v_lshlrev_b32_e32 v38, 16, v39
	v_and_b32_e32 v39, 0xffff0000, v39
	v_pk_add_f32 v[98:99], v[98:99], v[36:37]
	v_pk_add_f32 v[102:103], v[88:89], v[38:39]
	v_mov_b32_e32 v36, v156
	v_mov_b32_e32 v37, v157
	v_mov_b32_e32 v38, v158
	v_mov_b32_e32 v39, v159
	v_mov_b32_e32 v86, v160
	v_mov_b32_e32 v87, v161
	v_mov_b32_e32 v88, v162
	v_mov_b32_e32 v89, v163
	v_addc_co_u32_e32 v83, vcc, 0, v83, vcc
	s_waitcnt vmcnt(1)
	v_pk_fma_f32 v[6:7], v[102:103], v[38:39], v[6:7]
	s_waitcnt vmcnt(0)
	v_pk_fma_f32 v[10:11], v[100:101], v[88:89], v[10:11]
	v_pk_fma_f32 v[8:9], v[96:97], v[86:87], v[8:9]
	v_pk_fma_f32 v[4:5], v[98:99], v[36:37], v[4:5]
	v_cvt_pk_bf16_f32 v36, v8, v9
	v_cvt_pk_bf16_f32 v37, v10, v11
	s_nop 0
	v_cvt_pk_bf16_f32 v38, v4, v5
	v_cvt_pk_bf16_f32 v39, v6, v7
	global_store_dwordx4 v[82:83], v[36:39], off offset:1024
